# phases 7 and 8 GEMM hand-written: two output tiles per workgroup sharing the A rows, 9-slot 8KB LDS ring (K64 in two sub-steps), LDS-DMA ~2 sub-steps ahead; hand-written SwiGLU and residual epilogues
# speedup vs baseline: 1.1166x; 1.0558x over previous
.Lfin3_entry:
	s_mov_b32 s21, s60
	s_cmpk_gt_i32 s21, 0x1ff
	s_cbranch_scc1 .Lfin3_done
.Lfin3_tile:
	s_load_dwordx2 s[44:45], s[12:13], 0x180
	s_load_dwordx2 s[46:47], s[12:13], 0x138
	s_bfe_u32 s53, s21, 0x30006
	s_lshl_b32 s53, s53, 3
	s_and_b32 s56, s21, 7
	s_or_b32 s53, s53, s56
	s_lshl_b32 s53, s53, 7
	s_bfe_u32 s54, s21, 0x30003
	s_lshl_b32 s54, s54, 7
	v_lshrrev_b32_e32 v241, 6, v131
	v_and_b32_e32 v242, 63, v131
	s_nop 0
	v_readfirstlane_b32 s50, v241
	v_lshrrev_b32_e32 v241, 3, v242
	v_lshrrev_b32_e32 v243, 4, v242
	v_and_b32_e32 v244, 7, v242
	s_movk_i32 s56, 0x2c80
	v_xor_b32_e32 v245, v244, v243
	v_lshlrev_b32_e32 v245, 4, v245
	v_mad_u32_u24 v228, v241, s56, v245
	v_or_b32_e32 v243, 4, v243
	v_xor_b32_e32 v245, v244, v243
	v_lshlrev_b32_e32 v245, 4, v245
	v_add_u32_e32 v241, 8, v241
	v_mad_u32_u24 v230, v241, s56, v245
	v_add_u32_e32 v229, 0xb2000, v228
	v_add_u32_e32 v231, 0xb2000, v230
	v_and_b32_e32 v241, 15, v242
	v_lshrrev_b32_e32 v243, 4, v242
	v_bfe_u32 v244, v242, 1, 3
	v_xor_b32_e32 v244, v243, v244
	v_lshlrev_b32_e32 v244, 4, v244
	v_lshl_or_b32 v232, v241, 7, v244
	v_xor_b32_e32 v233, 64, v232
	s_lshr_b32 s56, s50, 1
	s_and_b32 s57, s50, 1
	s_mul_i32 s0, s56, 64*528
	s_lshl_b32 s1, s57, 8
	s_add_i32 s0, s0, s1
	s_add_i32 s0, s0, 16
	v_mul_u32_u24_e32 v243, 4*528, v243
	v_lshl_add_u32 v243, v241, 2, v243
	v_add_u32_e32 v238, s0, v243
	s_add_i32 s22, s56, 0
	s_lshl_b32 s22, s22, 13
	s_add_i32 s22, s22, 16
	s_add_i32 s28, s57, 2
	s_lshl_b32 s28, s28, 13
	s_add_i32 s28, s28, 16
	s_add_i32 s40, s57, 4
	s_lshl_b32 s40, s40, 13
	s_add_i32 s40, s40, 16
	s_add_i32 s23, s56, 6
	s_lshl_b32 s23, s23, 13
	s_add_i32 s23, s23, 16
	s_add_i32 s29, s57, 8
	s_cmp_ge_u32 s29, 9
	s_cselect_b32 s0, 9, 0
	s_sub_i32 s29, s29, s0
	s_lshl_b32 s29, s29, 13
	s_add_i32 s29, s29, 16
	s_add_i32 s41, s57, 1
	s_lshl_b32 s41, s41, 13
	s_add_i32 s41, s41, 16
	s_add_i32 s24, s56, 3
	s_lshl_b32 s24, s24, 13
	s_add_i32 s24, s24, 16
	s_add_i32 s30, s57, 5
	s_lshl_b32 s30, s30, 13
	s_add_i32 s30, s30, 16
	s_add_i32 s42, s57, 7
	s_lshl_b32 s42, s42, 13
	s_add_i32 s42, s42, 16
	s_lshl_b32 s56, s50, 4
	s_add_i32 s57, s53, s56
	s_add_i32 s56, s54, s56
	s_mul_i32 s57, s57, 0x2c80
	s_mul_i32 s56, s56, 0x2c80
	s_waitcnt lgkmcnt(0)
	s_add_u32 s44, s44, s57
	s_addc_u32 s45, s45, 0
	s_add_u32 s46, s46, s56
	s_addc_u32 s47, s47, 0
	s_add_u32 s48, s46, 0xb20000
	s_addc_u32 s49, s47, 0
	s_lshl_b32 s51, s50, 11
	s_add_i32 s51, s51, 16
	v_mov_b32_e32 v2, 0
	v_mov_b32_e32 v3, 0
	v_mov_b32_e32 v4, 0
	v_mov_b32_e32 v5, 0
	v_mov_b32_e32 v6, 0
	v_mov_b32_e32 v7, 0
	v_mov_b32_e32 v8, 0
	v_mov_b32_e32 v9, 0
	v_mov_b32_e32 v10, 0
	v_mov_b32_e32 v11, 0
	v_mov_b32_e32 v12, 0
	v_mov_b32_e32 v13, 0
	v_mov_b32_e32 v14, 0
	v_mov_b32_e32 v15, 0
	v_mov_b32_e32 v16, 0
	v_mov_b32_e32 v17, 0
	v_mov_b32_e32 v18, 0
	v_mov_b32_e32 v19, 0
	v_mov_b32_e32 v20, 0
	v_mov_b32_e32 v21, 0
	v_mov_b32_e32 v22, 0
	v_mov_b32_e32 v23, 0
	v_mov_b32_e32 v24, 0
	v_mov_b32_e32 v25, 0
	v_mov_b32_e32 v26, 0
	v_mov_b32_e32 v27, 0
	v_mov_b32_e32 v28, 0
	v_mov_b32_e32 v29, 0
	v_mov_b32_e32 v30, 0
	v_mov_b32_e32 v31, 0
	v_mov_b32_e32 v32, 0
	v_mov_b32_e32 v33, 0
	v_mov_b32_e32 v34, 0
	v_mov_b32_e32 v35, 0
	v_mov_b32_e32 v36, 0
	v_mov_b32_e32 v37, 0
	v_mov_b32_e32 v38, 0
	v_mov_b32_e32 v39, 0
	v_mov_b32_e32 v40, 0
	v_mov_b32_e32 v41, 0
	v_mov_b32_e32 v42, 0
	v_mov_b32_e32 v43, 0
	v_mov_b32_e32 v44, 0
	v_mov_b32_e32 v45, 0
	v_mov_b32_e32 v46, 0
	v_mov_b32_e32 v47, 0
	v_mov_b32_e32 v48, 0
	v_mov_b32_e32 v49, 0
	v_mov_b32_e32 v50, 0
	v_mov_b32_e32 v51, 0
	v_mov_b32_e32 v52, 0
	v_mov_b32_e32 v53, 0
	v_mov_b32_e32 v54, 0
	v_mov_b32_e32 v55, 0
	v_mov_b32_e32 v56, 0
	v_mov_b32_e32 v57, 0
	v_mov_b32_e32 v58, 0
	v_mov_b32_e32 v59, 0
	v_mov_b32_e32 v60, 0
	v_mov_b32_e32 v61, 0
	v_mov_b32_e32 v62, 0
	v_mov_b32_e32 v63, 0
	v_mov_b32_e32 v64, 0
	v_mov_b32_e32 v65, 0
	v_mov_b32_e32 v66, 0
	v_mov_b32_e32 v67, 0
	v_mov_b32_e32 v68, 0
	v_mov_b32_e32 v69, 0
	v_mov_b32_e32 v70, 0
	v_mov_b32_e32 v71, 0
	v_mov_b32_e32 v72, 0
	v_mov_b32_e32 v73, 0
	v_mov_b32_e32 v74, 0
	v_mov_b32_e32 v75, 0
	v_mov_b32_e32 v76, 0
	v_mov_b32_e32 v77, 0
	v_mov_b32_e32 v78, 0
	v_mov_b32_e32 v79, 0
	v_mov_b32_e32 v80, 0
	v_mov_b32_e32 v81, 0
	v_mov_b32_e32 v82, 0
	v_mov_b32_e32 v83, 0
	v_mov_b32_e32 v84, 0
	v_mov_b32_e32 v85, 0
	v_mov_b32_e32 v86, 0
	v_mov_b32_e32 v87, 0
	v_mov_b32_e32 v88, 0
	v_mov_b32_e32 v89, 0
	v_mov_b32_e32 v90, 0
	v_mov_b32_e32 v91, 0
	v_mov_b32_e32 v92, 0
	v_mov_b32_e32 v93, 0
	v_mov_b32_e32 v94, 0
	v_mov_b32_e32 v95, 0
	v_mov_b32_e32 v96, 0
	v_mov_b32_e32 v97, 0
	v_mov_b32_e32 v98, 0
	v_mov_b32_e32 v99, 0
	v_mov_b32_e32 v100, 0
	v_mov_b32_e32 v101, 0
	v_mov_b32_e32 v102, 0
	v_mov_b32_e32 v103, 0
	v_mov_b32_e32 v104, 0
	v_mov_b32_e32 v105, 0
	v_mov_b32_e32 v106, 0
	v_mov_b32_e32 v107, 0
	v_mov_b32_e32 v108, 0
	v_mov_b32_e32 v109, 0
	v_mov_b32_e32 v110, 0
	v_mov_b32_e32 v111, 0
	v_mov_b32_e32 v112, 0
	v_mov_b32_e32 v113, 0
	v_mov_b32_e32 v114, 0
	v_mov_b32_e32 v115, 0
	v_mov_b32_e32 v116, 0
	v_mov_b32_e32 v117, 0
	v_mov_b32_e32 v118, 0
	v_mov_b32_e32 v119, 0
	v_mov_b32_e32 v120, 0
	v_mov_b32_e32 v121, 0
	v_mov_b32_e32 v122, 0
	v_mov_b32_e32 v123, 0
	v_mov_b32_e32 v124, 0
	v_mov_b32_e32 v125, 0
	v_mov_b32_e32 v126, 0
	v_mov_b32_e32 v127, 0
	v_mov_b32_e32 v128, 0
	v_mov_b32_e32 v129, 0
	s_barrier
	s_mov_b32 m0, s51
	s_nop 0
	global_load_lds_dwordx4 v228, s[44:45]
	s_add_i32 m0, s51, 0x400
	s_nop 0
	global_load_lds_dwordx4 v230, s[44:45]
	s_add_i32 m0, s51, 0x2000
	s_nop 0
	global_load_lds_dwordx4 v229, s[44:45]
	s_add_i32 m0, s51, 0x2400
	s_nop 0
	global_load_lds_dwordx4 v231, s[44:45]
	s_add_i32 m0, s51, 0x4000
	s_nop 0
	global_load_lds_dwordx4 v228, s[46:47]
	s_add_i32 m0, s51, 0x4400
	s_nop 0
	global_load_lds_dwordx4 v230, s[46:47]
	s_add_i32 m0, s51, 0x6000
	s_nop 0
	global_load_lds_dwordx4 v229, s[46:47]
	s_add_i32 m0, s51, 0x6400
	s_nop 0
	global_load_lds_dwordx4 v231, s[46:47]
	s_add_i32 m0, s51, 0x8000
	s_nop 0
	global_load_lds_dwordx4 v228, s[48:49]
	s_add_i32 m0, s51, 0x8400
	s_nop 0
	global_load_lds_dwordx4 v230, s[48:49]
	s_add_i32 m0, s51, 0xa000
	s_nop 0
	global_load_lds_dwordx4 v229, s[48:49]
	s_add_i32 m0, s51, 0xa400
	s_nop 0
	global_load_lds_dwordx4 v231, s[48:49]
	v_add_u32_e32 v228, 0x80, v228
	v_add_u32_e32 v229, 0x80, v229
	v_add_u32_e32 v230, 0x80, v230
	v_add_u32_e32 v231, 0x80, v231
	s_waitcnt vmcnt(4)
	s_barrier
	s_mov_b32 s52, 0
.Lfin3_loop:
	s_add_i32 m0, s51, 0xc000
	s_nop 0
	global_load_lds_dwordx4 v228, s[44:45]
	s_add_i32 m0, s51, 0xc400
	s_nop 0
	global_load_lds_dwordx4 v230, s[44:45]
	s_add_i32 m0, s51, 0xe000
	s_nop 0
	global_load_lds_dwordx4 v229, s[44:45]
	s_add_i32 m0, s51, 0xe400
	s_nop 0
	global_load_lds_dwordx4 v231, s[44:45]
	s_add_i32 m0, s51, 0x10000
	s_nop 0
	global_load_lds_dwordx4 v228, s[46:47]
	s_add_i32 m0, s51, 0x10400
	s_nop 0
	global_load_lds_dwordx4 v230, s[46:47]
	v_add_u32_e32 v234, s22, v232
	v_add_u32_e32 v236, s28, v232
	v_add_u32_e32 v235, s22, v233
	v_add_u32_e32 v237, s28, v233
	ds_read_b128 v[136:139], v234
	ds_read_b128 v[140:143], v234 offset:2048
	ds_read_b128 v[144:147], v234 offset:4096
	ds_read_b128 v[148:151], v234 offset:6144
	ds_read_b128 v[188:191], v236
	ds_read_b128 v[196:199], v236 offset:2048
	ds_read_b128 v[200:203], v236 offset:4096
	ds_read_b128 v[204:207], v236 offset:6144
	ds_read_b128 v[172:175], v235
	ds_read_b128 v[176:179], v235 offset:2048
	ds_read_b128 v[180:183], v235 offset:4096
	ds_read_b128 v[184:187], v235 offset:6144
	ds_read_b128 v[212:215], v237
	ds_read_b128 v[216:219], v237 offset:2048
	ds_read_b128 v[220:223], v237 offset:4096
	ds_read_b128 v[224:227], v237 offset:6144
	s_waitcnt lgkmcnt(8)
	v_mfma_f32_16x16x32_bf16 v[2:5], v[136:139], v[188:191], v[2:5]
	v_mfma_f32_16x16x32_bf16 v[6:9], v[136:139], v[196:199], v[6:9]
	v_mfma_f32_16x16x32_bf16 v[10:13], v[136:139], v[200:203], v[10:13]
	v_mfma_f32_16x16x32_bf16 v[14:17], v[136:139], v[204:207], v[14:17]
	v_mfma_f32_16x16x32_bf16 v[18:21], v[140:143], v[188:191], v[18:21]
	v_mfma_f32_16x16x32_bf16 v[22:25], v[140:143], v[196:199], v[22:25]
	v_mfma_f32_16x16x32_bf16 v[26:29], v[140:143], v[200:203], v[26:29]
	v_mfma_f32_16x16x32_bf16 v[30:33], v[140:143], v[204:207], v[30:33]
	v_mfma_f32_16x16x32_bf16 v[34:37], v[144:147], v[188:191], v[34:37]
	v_mfma_f32_16x16x32_bf16 v[38:41], v[144:147], v[196:199], v[38:41]
	v_mfma_f32_16x16x32_bf16 v[42:45], v[144:147], v[200:203], v[42:45]
	v_mfma_f32_16x16x32_bf16 v[46:49], v[144:147], v[204:207], v[46:49]
	v_mfma_f32_16x16x32_bf16 v[50:53], v[148:151], v[188:191], v[50:53]
	v_mfma_f32_16x16x32_bf16 v[54:57], v[148:151], v[196:199], v[54:57]
	v_mfma_f32_16x16x32_bf16 v[58:61], v[148:151], v[200:203], v[58:61]
	v_mfma_f32_16x16x32_bf16 v[62:65], v[148:151], v[204:207], v[62:65]
	s_waitcnt lgkmcnt(0)
	v_mfma_f32_16x16x32_bf16 v[2:5], v[172:175], v[212:215], v[2:5]
	v_mfma_f32_16x16x32_bf16 v[6:9], v[172:175], v[216:219], v[6:9]
	v_mfma_f32_16x16x32_bf16 v[10:13], v[172:175], v[220:223], v[10:13]
	v_mfma_f32_16x16x32_bf16 v[14:17], v[172:175], v[224:227], v[14:17]
	v_mfma_f32_16x16x32_bf16 v[18:21], v[176:179], v[212:215], v[18:21]
	v_mfma_f32_16x16x32_bf16 v[22:25], v[176:179], v[216:219], v[22:25]
	v_mfma_f32_16x16x32_bf16 v[26:29], v[176:179], v[220:223], v[26:29]
	v_mfma_f32_16x16x32_bf16 v[30:33], v[176:179], v[224:227], v[30:33]
	v_mfma_f32_16x16x32_bf16 v[34:37], v[180:183], v[212:215], v[34:37]
	v_mfma_f32_16x16x32_bf16 v[38:41], v[180:183], v[216:219], v[38:41]
	v_mfma_f32_16x16x32_bf16 v[42:45], v[180:183], v[220:223], v[42:45]
	v_mfma_f32_16x16x32_bf16 v[46:49], v[180:183], v[224:227], v[46:49]
	v_mfma_f32_16x16x32_bf16 v[50:53], v[184:187], v[212:215], v[50:53]
	v_mfma_f32_16x16x32_bf16 v[54:57], v[184:187], v[216:219], v[54:57]
	v_mfma_f32_16x16x32_bf16 v[58:61], v[184:187], v[220:223], v[58:61]
	v_mfma_f32_16x16x32_bf16 v[62:65], v[184:187], v[224:227], v[62:65]
	s_waitcnt vmcnt(6)
	s_barrier
	s_mov_b32 m0, s51
	s_nop 0
	global_load_lds_dwordx4 v229, s[46:47]
	s_add_i32 m0, s51, 0x400
	s_nop 0
	global_load_lds_dwordx4 v231, s[46:47]
	s_add_i32 m0, s51, 0x2000
	s_nop 0
	global_load_lds_dwordx4 v228, s[48:49]
	s_add_i32 m0, s51, 0x2400
	s_nop 0
	global_load_lds_dwordx4 v230, s[48:49]
	s_add_i32 m0, s51, 0x4000
	s_nop 0
	global_load_lds_dwordx4 v229, s[48:49]
	s_add_i32 m0, s51, 0x4400
	s_nop 0
	global_load_lds_dwordx4 v231, s[48:49]
	v_add_u32_e32 v236, s40, v232
	v_add_u32_e32 v237, s40, v233
	ds_read_b128 v[188:191], v236
	ds_read_b128 v[196:199], v236 offset:2048
	ds_read_b128 v[200:203], v236 offset:4096
	ds_read_b128 v[204:207], v236 offset:6144
	ds_read_b128 v[212:215], v237
	ds_read_b128 v[216:219], v237 offset:2048
	ds_read_b128 v[220:223], v237 offset:4096
	ds_read_b128 v[224:227], v237 offset:6144
	s_waitcnt lgkmcnt(4)
	v_mfma_f32_16x16x32_bf16 v[66:69], v[136:139], v[188:191], v[66:69]
	v_mfma_f32_16x16x32_bf16 v[70:73], v[136:139], v[196:199], v[70:73]
	v_mfma_f32_16x16x32_bf16 v[74:77], v[136:139], v[200:203], v[74:77]
	v_mfma_f32_16x16x32_bf16 v[78:81], v[136:139], v[204:207], v[78:81]
	v_mfma_f32_16x16x32_bf16 v[82:85], v[140:143], v[188:191], v[82:85]
	v_mfma_f32_16x16x32_bf16 v[86:89], v[140:143], v[196:199], v[86:89]
	v_mfma_f32_16x16x32_bf16 v[90:93], v[140:143], v[200:203], v[90:93]
	v_mfma_f32_16x16x32_bf16 v[94:97], v[140:143], v[204:207], v[94:97]
	v_mfma_f32_16x16x32_bf16 v[98:101], v[144:147], v[188:191], v[98:101]
	v_mfma_f32_16x16x32_bf16 v[102:105], v[144:147], v[196:199], v[102:105]
	v_mfma_f32_16x16x32_bf16 v[106:109], v[144:147], v[200:203], v[106:109]
	v_mfma_f32_16x16x32_bf16 v[110:113], v[144:147], v[204:207], v[110:113]
	v_mfma_f32_16x16x32_bf16 v[114:117], v[148:151], v[188:191], v[114:117]
	v_mfma_f32_16x16x32_bf16 v[118:121], v[148:151], v[196:199], v[118:121]
	v_mfma_f32_16x16x32_bf16 v[122:125], v[148:151], v[200:203], v[122:125]
	v_mfma_f32_16x16x32_bf16 v[126:129], v[148:151], v[204:207], v[126:129]
	s_waitcnt lgkmcnt(0)
	v_mfma_f32_16x16x32_bf16 v[66:69], v[172:175], v[212:215], v[66:69]
	v_mfma_f32_16x16x32_bf16 v[70:73], v[172:175], v[216:219], v[70:73]
	v_mfma_f32_16x16x32_bf16 v[74:77], v[172:175], v[220:223], v[74:77]
	v_mfma_f32_16x16x32_bf16 v[78:81], v[172:175], v[224:227], v[78:81]
	v_mfma_f32_16x16x32_bf16 v[82:85], v[176:179], v[212:215], v[82:85]
	v_mfma_f32_16x16x32_bf16 v[86:89], v[176:179], v[216:219], v[86:89]
	v_mfma_f32_16x16x32_bf16 v[90:93], v[176:179], v[220:223], v[90:93]
	v_mfma_f32_16x16x32_bf16 v[94:97], v[176:179], v[224:227], v[94:97]
	v_mfma_f32_16x16x32_bf16 v[98:101], v[180:183], v[212:215], v[98:101]
	v_mfma_f32_16x16x32_bf16 v[102:105], v[180:183], v[216:219], v[102:105]
	v_mfma_f32_16x16x32_bf16 v[106:109], v[180:183], v[220:223], v[106:109]
	v_mfma_f32_16x16x32_bf16 v[110:113], v[180:183], v[224:227], v[110:113]
	v_mfma_f32_16x16x32_bf16 v[114:117], v[184:187], v[212:215], v[114:117]
	v_mfma_f32_16x16x32_bf16 v[118:121], v[184:187], v[216:219], v[118:121]
	v_mfma_f32_16x16x32_bf16 v[122:125], v[184:187], v[220:223], v[122:125]
	v_mfma_f32_16x16x32_bf16 v[126:129], v[184:187], v[224:227], v[126:129]
	v_add_u32_e32 v228, 0x80, v228
	v_add_u32_e32 v229, 0x80, v229
	v_add_u32_e32 v230, 0x80, v230
	v_add_u32_e32 v231, 0x80, v231
	s_waitcnt vmcnt(4)
	s_barrier
	s_add_i32 m0, s51, 0x6000
	s_nop 0
	global_load_lds_dwordx4 v228, s[44:45]
	s_add_i32 m0, s51, 0x6400
	s_nop 0
	global_load_lds_dwordx4 v230, s[44:45]
	s_add_i32 m0, s51, 0x8000
	s_nop 0
	global_load_lds_dwordx4 v229, s[44:45]
	s_add_i32 m0, s51, 0x8400
	s_nop 0
	global_load_lds_dwordx4 v231, s[44:45]
	s_add_i32 m0, s51, 0xa000
	s_nop 0
	global_load_lds_dwordx4 v228, s[46:47]
	s_add_i32 m0, s51, 0xa400
	s_nop 0
	global_load_lds_dwordx4 v230, s[46:47]
	v_add_u32_e32 v234, s23, v232
	v_add_u32_e32 v236, s29, v232
	v_add_u32_e32 v235, s23, v233
	v_add_u32_e32 v237, s29, v233
	ds_read_b128 v[136:139], v234
	ds_read_b128 v[140:143], v234 offset:2048
	ds_read_b128 v[144:147], v234 offset:4096
	ds_read_b128 v[148:151], v234 offset:6144
	ds_read_b128 v[188:191], v236
	ds_read_b128 v[196:199], v236 offset:2048
	ds_read_b128 v[200:203], v236 offset:4096
	ds_read_b128 v[204:207], v236 offset:6144
	ds_read_b128 v[172:175], v235
	ds_read_b128 v[176:179], v235 offset:2048
	ds_read_b128 v[180:183], v235 offset:4096
	ds_read_b128 v[184:187], v235 offset:6144
	ds_read_b128 v[212:215], v237
	ds_read_b128 v[216:219], v237 offset:2048
	ds_read_b128 v[220:223], v237 offset:4096
	ds_read_b128 v[224:227], v237 offset:6144
	s_waitcnt lgkmcnt(8)
	v_mfma_f32_16x16x32_bf16 v[2:5], v[136:139], v[188:191], v[2:5]
	v_mfma_f32_16x16x32_bf16 v[6:9], v[136:139], v[196:199], v[6:9]
	v_mfma_f32_16x16x32_bf16 v[10:13], v[136:139], v[200:203], v[10:13]
	v_mfma_f32_16x16x32_bf16 v[14:17], v[136:139], v[204:207], v[14:17]
	v_mfma_f32_16x16x32_bf16 v[18:21], v[140:143], v[188:191], v[18:21]
	v_mfma_f32_16x16x32_bf16 v[22:25], v[140:143], v[196:199], v[22:25]
	v_mfma_f32_16x16x32_bf16 v[26:29], v[140:143], v[200:203], v[26:29]
	v_mfma_f32_16x16x32_bf16 v[30:33], v[140:143], v[204:207], v[30:33]
	v_mfma_f32_16x16x32_bf16 v[34:37], v[144:147], v[188:191], v[34:37]
	v_mfma_f32_16x16x32_bf16 v[38:41], v[144:147], v[196:199], v[38:41]
	v_mfma_f32_16x16x32_bf16 v[42:45], v[144:147], v[200:203], v[42:45]
	v_mfma_f32_16x16x32_bf16 v[46:49], v[144:147], v[204:207], v[46:49]
	v_mfma_f32_16x16x32_bf16 v[50:53], v[148:151], v[188:191], v[50:53]
	v_mfma_f32_16x16x32_bf16 v[54:57], v[148:151], v[196:199], v[54:57]
	v_mfma_f32_16x16x32_bf16 v[58:61], v[148:151], v[200:203], v[58:61]
	v_mfma_f32_16x16x32_bf16 v[62:65], v[148:151], v[204:207], v[62:65]
	s_waitcnt lgkmcnt(0)
	v_mfma_f32_16x16x32_bf16 v[2:5], v[172:175], v[212:215], v[2:5]
	v_mfma_f32_16x16x32_bf16 v[6:9], v[172:175], v[216:219], v[6:9]
	v_mfma_f32_16x16x32_bf16 v[10:13], v[172:175], v[220:223], v[10:13]
	v_mfma_f32_16x16x32_bf16 v[14:17], v[172:175], v[224:227], v[14:17]
	v_mfma_f32_16x16x32_bf16 v[18:21], v[176:179], v[212:215], v[18:21]
	v_mfma_f32_16x16x32_bf16 v[22:25], v[176:179], v[216:219], v[22:25]
	v_mfma_f32_16x16x32_bf16 v[26:29], v[176:179], v[220:223], v[26:29]
	v_mfma_f32_16x16x32_bf16 v[30:33], v[176:179], v[224:227], v[30:33]
	v_mfma_f32_16x16x32_bf16 v[34:37], v[180:183], v[212:215], v[34:37]
	v_mfma_f32_16x16x32_bf16 v[38:41], v[180:183], v[216:219], v[38:41]
	v_mfma_f32_16x16x32_bf16 v[42:45], v[180:183], v[220:223], v[42:45]
	v_mfma_f32_16x16x32_bf16 v[46:49], v[180:183], v[224:227], v[46:49]
	v_mfma_f32_16x16x32_bf16 v[50:53], v[184:187], v[212:215], v[50:53]
	v_mfma_f32_16x16x32_bf16 v[54:57], v[184:187], v[216:219], v[54:57]
	v_mfma_f32_16x16x32_bf16 v[58:61], v[184:187], v[220:223], v[58:61]
	v_mfma_f32_16x16x32_bf16 v[62:65], v[184:187], v[224:227], v[62:65]
	s_waitcnt vmcnt(6)
	s_barrier
	s_add_i32 m0, s51, 0xc000
	s_nop 0
	global_load_lds_dwordx4 v229, s[46:47]
	s_add_i32 m0, s51, 0xc400
	s_nop 0
	global_load_lds_dwordx4 v231, s[46:47]
	s_add_i32 m0, s51, 0xe000
	s_nop 0
	global_load_lds_dwordx4 v228, s[48:49]
	s_add_i32 m0, s51, 0xe400
	s_nop 0
	global_load_lds_dwordx4 v230, s[48:49]
	s_add_i32 m0, s51, 0x10000
	s_nop 0
	global_load_lds_dwordx4 v229, s[48:49]
	s_add_i32 m0, s51, 0x10400
	s_nop 0
	global_load_lds_dwordx4 v231, s[48:49]
	v_add_u32_e32 v236, s41, v232
	v_add_u32_e32 v237, s41, v233
	ds_read_b128 v[188:191], v236
	ds_read_b128 v[196:199], v236 offset:2048
	ds_read_b128 v[200:203], v236 offset:4096
	ds_read_b128 v[204:207], v236 offset:6144
	ds_read_b128 v[212:215], v237
	ds_read_b128 v[216:219], v237 offset:2048
	ds_read_b128 v[220:223], v237 offset:4096
	ds_read_b128 v[224:227], v237 offset:6144
	s_waitcnt lgkmcnt(4)
	v_mfma_f32_16x16x32_bf16 v[66:69], v[136:139], v[188:191], v[66:69]
	v_mfma_f32_16x16x32_bf16 v[70:73], v[136:139], v[196:199], v[70:73]
	v_mfma_f32_16x16x32_bf16 v[74:77], v[136:139], v[200:203], v[74:77]
	v_mfma_f32_16x16x32_bf16 v[78:81], v[136:139], v[204:207], v[78:81]
	v_mfma_f32_16x16x32_bf16 v[82:85], v[140:143], v[188:191], v[82:85]
	v_mfma_f32_16x16x32_bf16 v[86:89], v[140:143], v[196:199], v[86:89]
	v_mfma_f32_16x16x32_bf16 v[90:93], v[140:143], v[200:203], v[90:93]
	v_mfma_f32_16x16x32_bf16 v[94:97], v[140:143], v[204:207], v[94:97]
	v_mfma_f32_16x16x32_bf16 v[98:101], v[144:147], v[188:191], v[98:101]
	v_mfma_f32_16x16x32_bf16 v[102:105], v[144:147], v[196:199], v[102:105]
	v_mfma_f32_16x16x32_bf16 v[106:109], v[144:147], v[200:203], v[106:109]
	v_mfma_f32_16x16x32_bf16 v[110:113], v[144:147], v[204:207], v[110:113]
	v_mfma_f32_16x16x32_bf16 v[114:117], v[148:151], v[188:191], v[114:117]
	v_mfma_f32_16x16x32_bf16 v[118:121], v[148:151], v[196:199], v[118:121]
	v_mfma_f32_16x16x32_bf16 v[122:125], v[148:151], v[200:203], v[122:125]
	v_mfma_f32_16x16x32_bf16 v[126:129], v[148:151], v[204:207], v[126:129]
	s_waitcnt lgkmcnt(0)
	v_mfma_f32_16x16x32_bf16 v[66:69], v[172:175], v[212:215], v[66:69]
	v_mfma_f32_16x16x32_bf16 v[70:73], v[172:175], v[216:219], v[70:73]
	v_mfma_f32_16x16x32_bf16 v[74:77], v[172:175], v[220:223], v[74:77]
	v_mfma_f32_16x16x32_bf16 v[78:81], v[172:175], v[224:227], v[78:81]
	v_mfma_f32_16x16x32_bf16 v[82:85], v[176:179], v[212:215], v[82:85]
	v_mfma_f32_16x16x32_bf16 v[86:89], v[176:179], v[216:219], v[86:89]
	v_mfma_f32_16x16x32_bf16 v[90:93], v[176:179], v[220:223], v[90:93]
	v_mfma_f32_16x16x32_bf16 v[94:97], v[176:179], v[224:227], v[94:97]
	v_mfma_f32_16x16x32_bf16 v[98:101], v[180:183], v[212:215], v[98:101]
	v_mfma_f32_16x16x32_bf16 v[102:105], v[180:183], v[216:219], v[102:105]
	v_mfma_f32_16x16x32_bf16 v[106:109], v[180:183], v[220:223], v[106:109]
	v_mfma_f32_16x16x32_bf16 v[110:113], v[180:183], v[224:227], v[110:113]
	v_mfma_f32_16x16x32_bf16 v[114:117], v[184:187], v[212:215], v[114:117]
	v_mfma_f32_16x16x32_bf16 v[118:121], v[184:187], v[216:219], v[118:121]
	v_mfma_f32_16x16x32_bf16 v[122:125], v[184:187], v[220:223], v[122:125]
	v_mfma_f32_16x16x32_bf16 v[126:129], v[184:187], v[224:227], v[126:129]
	v_add_u32_e32 v228, 0x80, v228
	v_add_u32_e32 v229, 0x80, v229
	v_add_u32_e32 v230, 0x80, v230
	v_add_u32_e32 v231, 0x80, v231
	s_waitcnt vmcnt(4)
	s_barrier
	s_mov_b32 m0, s51
	s_nop 0
	global_load_lds_dwordx4 v228, s[44:45]
	s_add_i32 m0, s51, 0x400
	s_nop 0
	global_load_lds_dwordx4 v230, s[44:45]
	s_add_i32 m0, s51, 0x2000
	s_nop 0
	global_load_lds_dwordx4 v229, s[44:45]
	s_add_i32 m0, s51, 0x2400
	s_nop 0
	global_load_lds_dwordx4 v231, s[44:45]
	s_add_i32 m0, s51, 0x4000
	s_nop 0
	global_load_lds_dwordx4 v228, s[46:47]
	s_add_i32 m0, s51, 0x4400
	s_nop 0
	global_load_lds_dwordx4 v230, s[46:47]
	v_add_u32_e32 v234, s24, v232
	v_add_u32_e32 v236, s30, v232
	v_add_u32_e32 v235, s24, v233
	v_add_u32_e32 v237, s30, v233
	ds_read_b128 v[136:139], v234
	ds_read_b128 v[140:143], v234 offset:2048
	ds_read_b128 v[144:147], v234 offset:4096
	ds_read_b128 v[148:151], v234 offset:6144
	ds_read_b128 v[188:191], v236
	ds_read_b128 v[196:199], v236 offset:2048
	ds_read_b128 v[200:203], v236 offset:4096
	ds_read_b128 v[204:207], v236 offset:6144
	ds_read_b128 v[172:175], v235
	ds_read_b128 v[176:179], v235 offset:2048
	ds_read_b128 v[180:183], v235 offset:4096
	ds_read_b128 v[184:187], v235 offset:6144
	ds_read_b128 v[212:215], v237
	ds_read_b128 v[216:219], v237 offset:2048
	ds_read_b128 v[220:223], v237 offset:4096
	ds_read_b128 v[224:227], v237 offset:6144
	s_waitcnt lgkmcnt(8)
	v_mfma_f32_16x16x32_bf16 v[2:5], v[136:139], v[188:191], v[2:5]
	v_mfma_f32_16x16x32_bf16 v[6:9], v[136:139], v[196:199], v[6:9]
	v_mfma_f32_16x16x32_bf16 v[10:13], v[136:139], v[200:203], v[10:13]
	v_mfma_f32_16x16x32_bf16 v[14:17], v[136:139], v[204:207], v[14:17]
	v_mfma_f32_16x16x32_bf16 v[18:21], v[140:143], v[188:191], v[18:21]
	v_mfma_f32_16x16x32_bf16 v[22:25], v[140:143], v[196:199], v[22:25]
	v_mfma_f32_16x16x32_bf16 v[26:29], v[140:143], v[200:203], v[26:29]
	v_mfma_f32_16x16x32_bf16 v[30:33], v[140:143], v[204:207], v[30:33]
	v_mfma_f32_16x16x32_bf16 v[34:37], v[144:147], v[188:191], v[34:37]
	v_mfma_f32_16x16x32_bf16 v[38:41], v[144:147], v[196:199], v[38:41]
	v_mfma_f32_16x16x32_bf16 v[42:45], v[144:147], v[200:203], v[42:45]
	v_mfma_f32_16x16x32_bf16 v[46:49], v[144:147], v[204:207], v[46:49]
	v_mfma_f32_16x16x32_bf16 v[50:53], v[148:151], v[188:191], v[50:53]
	v_mfma_f32_16x16x32_bf16 v[54:57], v[148:151], v[196:199], v[54:57]
	v_mfma_f32_16x16x32_bf16 v[58:61], v[148:151], v[200:203], v[58:61]
	v_mfma_f32_16x16x32_bf16 v[62:65], v[148:151], v[204:207], v[62:65]
	s_waitcnt lgkmcnt(0)
	v_mfma_f32_16x16x32_bf16 v[2:5], v[172:175], v[212:215], v[2:5]
	v_mfma_f32_16x16x32_bf16 v[6:9], v[172:175], v[216:219], v[6:9]
	v_mfma_f32_16x16x32_bf16 v[10:13], v[172:175], v[220:223], v[10:13]
	v_mfma_f32_16x16x32_bf16 v[14:17], v[172:175], v[224:227], v[14:17]
	v_mfma_f32_16x16x32_bf16 v[18:21], v[176:179], v[212:215], v[18:21]
	v_mfma_f32_16x16x32_bf16 v[22:25], v[176:179], v[216:219], v[22:25]
	v_mfma_f32_16x16x32_bf16 v[26:29], v[176:179], v[220:223], v[26:29]
	v_mfma_f32_16x16x32_bf16 v[30:33], v[176:179], v[224:227], v[30:33]
	v_mfma_f32_16x16x32_bf16 v[34:37], v[180:183], v[212:215], v[34:37]
	v_mfma_f32_16x16x32_bf16 v[38:41], v[180:183], v[216:219], v[38:41]
	v_mfma_f32_16x16x32_bf16 v[42:45], v[180:183], v[220:223], v[42:45]
	v_mfma_f32_16x16x32_bf16 v[46:49], v[180:183], v[224:227], v[46:49]
	v_mfma_f32_16x16x32_bf16 v[50:53], v[184:187], v[212:215], v[50:53]
	v_mfma_f32_16x16x32_bf16 v[54:57], v[184:187], v[216:219], v[54:57]
	v_mfma_f32_16x16x32_bf16 v[58:61], v[184:187], v[220:223], v[58:61]
	v_mfma_f32_16x16x32_bf16 v[62:65], v[184:187], v[224:227], v[62:65]
	s_waitcnt vmcnt(6)
	s_barrier
	s_add_i32 m0, s51, 0x6000
	s_nop 0
	global_load_lds_dwordx4 v229, s[46:47]
	s_add_i32 m0, s51, 0x6400
	s_nop 0
	global_load_lds_dwordx4 v231, s[46:47]
	s_add_i32 m0, s51, 0x8000
	s_nop 0
	global_load_lds_dwordx4 v228, s[48:49]
	s_add_i32 m0, s51, 0x8400
	s_nop 0
	global_load_lds_dwordx4 v230, s[48:49]
	s_add_i32 m0, s51, 0xa000
	s_nop 0
	global_load_lds_dwordx4 v229, s[48:49]
	s_add_i32 m0, s51, 0xa400
	s_nop 0
	global_load_lds_dwordx4 v231, s[48:49]
	v_add_u32_e32 v236, s42, v232
	v_add_u32_e32 v237, s42, v233
	ds_read_b128 v[188:191], v236
	ds_read_b128 v[196:199], v236 offset:2048
	ds_read_b128 v[200:203], v236 offset:4096
	ds_read_b128 v[204:207], v236 offset:6144
	ds_read_b128 v[212:215], v237
	ds_read_b128 v[216:219], v237 offset:2048
	ds_read_b128 v[220:223], v237 offset:4096
	ds_read_b128 v[224:227], v237 offset:6144
	s_waitcnt lgkmcnt(4)
	v_mfma_f32_16x16x32_bf16 v[66:69], v[136:139], v[188:191], v[66:69]
	v_mfma_f32_16x16x32_bf16 v[70:73], v[136:139], v[196:199], v[70:73]
	v_mfma_f32_16x16x32_bf16 v[74:77], v[136:139], v[200:203], v[74:77]
	v_mfma_f32_16x16x32_bf16 v[78:81], v[136:139], v[204:207], v[78:81]
	v_mfma_f32_16x16x32_bf16 v[82:85], v[140:143], v[188:191], v[82:85]
	v_mfma_f32_16x16x32_bf16 v[86:89], v[140:143], v[196:199], v[86:89]
	v_mfma_f32_16x16x32_bf16 v[90:93], v[140:143], v[200:203], v[90:93]
	v_mfma_f32_16x16x32_bf16 v[94:97], v[140:143], v[204:207], v[94:97]
	v_mfma_f32_16x16x32_bf16 v[98:101], v[144:147], v[188:191], v[98:101]
	v_mfma_f32_16x16x32_bf16 v[102:105], v[144:147], v[196:199], v[102:105]
	v_mfma_f32_16x16x32_bf16 v[106:109], v[144:147], v[200:203], v[106:109]
	v_mfma_f32_16x16x32_bf16 v[110:113], v[144:147], v[204:207], v[110:113]
	v_mfma_f32_16x16x32_bf16 v[114:117], v[148:151], v[188:191], v[114:117]
	v_mfma_f32_16x16x32_bf16 v[118:121], v[148:151], v[196:199], v[118:121]
	v_mfma_f32_16x16x32_bf16 v[122:125], v[148:151], v[200:203], v[122:125]
	v_mfma_f32_16x16x32_bf16 v[126:129], v[148:151], v[204:207], v[126:129]
	s_waitcnt lgkmcnt(0)
	v_mfma_f32_16x16x32_bf16 v[66:69], v[172:175], v[212:215], v[66:69]
	v_mfma_f32_16x16x32_bf16 v[70:73], v[172:175], v[216:219], v[70:73]
	v_mfma_f32_16x16x32_bf16 v[74:77], v[172:175], v[220:223], v[74:77]
	v_mfma_f32_16x16x32_bf16 v[78:81], v[172:175], v[224:227], v[78:81]
	v_mfma_f32_16x16x32_bf16 v[82:85], v[176:179], v[212:215], v[82:85]
	v_mfma_f32_16x16x32_bf16 v[86:89], v[176:179], v[216:219], v[86:89]
	v_mfma_f32_16x16x32_bf16 v[90:93], v[176:179], v[220:223], v[90:93]
	v_mfma_f32_16x16x32_bf16 v[94:97], v[176:179], v[224:227], v[94:97]
	v_mfma_f32_16x16x32_bf16 v[98:101], v[180:183], v[212:215], v[98:101]
	v_mfma_f32_16x16x32_bf16 v[102:105], v[180:183], v[216:219], v[102:105]
	v_mfma_f32_16x16x32_bf16 v[106:109], v[180:183], v[220:223], v[106:109]
	v_mfma_f32_16x16x32_bf16 v[110:113], v[180:183], v[224:227], v[110:113]
	v_mfma_f32_16x16x32_bf16 v[114:117], v[184:187], v[212:215], v[114:117]
	v_mfma_f32_16x16x32_bf16 v[118:121], v[184:187], v[216:219], v[118:121]
	v_mfma_f32_16x16x32_bf16 v[122:125], v[184:187], v[220:223], v[122:125]
	v_mfma_f32_16x16x32_bf16 v[126:129], v[184:187], v[224:227], v[126:129]
	v_add_u32_e32 v228, 0x80, v228
	v_add_u32_e32 v229, 0x80, v229
	v_add_u32_e32 v230, 0x80, v230
	v_add_u32_e32 v231, 0x80, v231
	s_waitcnt vmcnt(4)
	s_barrier
	s_add_i32 s52, s52, 1
	s_cmp_lt_u32 s52, 29
	s_cbranch_scc1 .Lfin3_loop
	v_add_u32_e32 v234, s22, v232
	v_add_u32_e32 v236, s28, v232
	v_add_u32_e32 v235, s22, v233
	v_add_u32_e32 v237, s28, v233
	ds_read_b128 v[136:139], v234
	ds_read_b128 v[140:143], v234 offset:2048
	ds_read_b128 v[144:147], v234 offset:4096
	ds_read_b128 v[148:151], v234 offset:6144
	ds_read_b128 v[188:191], v236
	ds_read_b128 v[196:199], v236 offset:2048
	ds_read_b128 v[200:203], v236 offset:4096
	ds_read_b128 v[204:207], v236 offset:6144
	ds_read_b128 v[172:175], v235
	ds_read_b128 v[176:179], v235 offset:2048
	ds_read_b128 v[180:183], v235 offset:4096
	ds_read_b128 v[184:187], v235 offset:6144
	ds_read_b128 v[212:215], v237
	ds_read_b128 v[216:219], v237 offset:2048
	ds_read_b128 v[220:223], v237 offset:4096
	ds_read_b128 v[224:227], v237 offset:6144
	s_waitcnt lgkmcnt(8)
	v_mfma_f32_16x16x32_bf16 v[2:5], v[136:139], v[188:191], v[2:5]
	v_mfma_f32_16x16x32_bf16 v[6:9], v[136:139], v[196:199], v[6:9]
	v_mfma_f32_16x16x32_bf16 v[10:13], v[136:139], v[200:203], v[10:13]
	v_mfma_f32_16x16x32_bf16 v[14:17], v[136:139], v[204:207], v[14:17]
	v_mfma_f32_16x16x32_bf16 v[18:21], v[140:143], v[188:191], v[18:21]
	v_mfma_f32_16x16x32_bf16 v[22:25], v[140:143], v[196:199], v[22:25]
	v_mfma_f32_16x16x32_bf16 v[26:29], v[140:143], v[200:203], v[26:29]
	v_mfma_f32_16x16x32_bf16 v[30:33], v[140:143], v[204:207], v[30:33]
	v_mfma_f32_16x16x32_bf16 v[34:37], v[144:147], v[188:191], v[34:37]
	v_mfma_f32_16x16x32_bf16 v[38:41], v[144:147], v[196:199], v[38:41]
	v_mfma_f32_16x16x32_bf16 v[42:45], v[144:147], v[200:203], v[42:45]
	v_mfma_f32_16x16x32_bf16 v[46:49], v[144:147], v[204:207], v[46:49]
	v_mfma_f32_16x16x32_bf16 v[50:53], v[148:151], v[188:191], v[50:53]
	v_mfma_f32_16x16x32_bf16 v[54:57], v[148:151], v[196:199], v[54:57]
	v_mfma_f32_16x16x32_bf16 v[58:61], v[148:151], v[200:203], v[58:61]
	v_mfma_f32_16x16x32_bf16 v[62:65], v[148:151], v[204:207], v[62:65]
	s_waitcnt lgkmcnt(0)
	v_mfma_f32_16x16x32_bf16 v[2:5], v[172:175], v[212:215], v[2:5]
	v_mfma_f32_16x16x32_bf16 v[6:9], v[172:175], v[216:219], v[6:9]
	v_mfma_f32_16x16x32_bf16 v[10:13], v[172:175], v[220:223], v[10:13]
	v_mfma_f32_16x16x32_bf16 v[14:17], v[172:175], v[224:227], v[14:17]
	v_mfma_f32_16x16x32_bf16 v[18:21], v[176:179], v[212:215], v[18:21]
	v_mfma_f32_16x16x32_bf16 v[22:25], v[176:179], v[216:219], v[22:25]
	v_mfma_f32_16x16x32_bf16 v[26:29], v[176:179], v[220:223], v[26:29]
	v_mfma_f32_16x16x32_bf16 v[30:33], v[176:179], v[224:227], v[30:33]
	v_mfma_f32_16x16x32_bf16 v[34:37], v[180:183], v[212:215], v[34:37]
	v_mfma_f32_16x16x32_bf16 v[38:41], v[180:183], v[216:219], v[38:41]
	v_mfma_f32_16x16x32_bf16 v[42:45], v[180:183], v[220:223], v[42:45]
	v_mfma_f32_16x16x32_bf16 v[46:49], v[180:183], v[224:227], v[46:49]
	v_mfma_f32_16x16x32_bf16 v[50:53], v[184:187], v[212:215], v[50:53]
	v_mfma_f32_16x16x32_bf16 v[54:57], v[184:187], v[216:219], v[54:57]
	v_mfma_f32_16x16x32_bf16 v[58:61], v[184:187], v[220:223], v[58:61]
	v_mfma_f32_16x16x32_bf16 v[62:65], v[184:187], v[224:227], v[62:65]
	s_waitcnt vmcnt(0)
	s_barrier
	v_add_u32_e32 v236, s40, v232
	v_add_u32_e32 v237, s40, v233
	ds_read_b128 v[188:191], v236
	ds_read_b128 v[196:199], v236 offset:2048
	ds_read_b128 v[200:203], v236 offset:4096
	ds_read_b128 v[204:207], v236 offset:6144
	ds_read_b128 v[212:215], v237
	ds_read_b128 v[216:219], v237 offset:2048
	ds_read_b128 v[220:223], v237 offset:4096
	ds_read_b128 v[224:227], v237 offset:6144
	s_waitcnt lgkmcnt(4)
	v_mfma_f32_16x16x32_bf16 v[66:69], v[136:139], v[188:191], v[66:69]
	v_mfma_f32_16x16x32_bf16 v[70:73], v[136:139], v[196:199], v[70:73]
	v_mfma_f32_16x16x32_bf16 v[74:77], v[136:139], v[200:203], v[74:77]
	v_mfma_f32_16x16x32_bf16 v[78:81], v[136:139], v[204:207], v[78:81]
	v_mfma_f32_16x16x32_bf16 v[82:85], v[140:143], v[188:191], v[82:85]
	v_mfma_f32_16x16x32_bf16 v[86:89], v[140:143], v[196:199], v[86:89]
	v_mfma_f32_16x16x32_bf16 v[90:93], v[140:143], v[200:203], v[90:93]
	v_mfma_f32_16x16x32_bf16 v[94:97], v[140:143], v[204:207], v[94:97]
	v_mfma_f32_16x16x32_bf16 v[98:101], v[144:147], v[188:191], v[98:101]
	v_mfma_f32_16x16x32_bf16 v[102:105], v[144:147], v[196:199], v[102:105]
	v_mfma_f32_16x16x32_bf16 v[106:109], v[144:147], v[200:203], v[106:109]
	v_mfma_f32_16x16x32_bf16 v[110:113], v[144:147], v[204:207], v[110:113]
	v_mfma_f32_16x16x32_bf16 v[114:117], v[148:151], v[188:191], v[114:117]
	v_mfma_f32_16x16x32_bf16 v[118:121], v[148:151], v[196:199], v[118:121]
	v_mfma_f32_16x16x32_bf16 v[122:125], v[148:151], v[200:203], v[122:125]
	v_mfma_f32_16x16x32_bf16 v[126:129], v[148:151], v[204:207], v[126:129]
	s_waitcnt lgkmcnt(0)
	v_mfma_f32_16x16x32_bf16 v[66:69], v[172:175], v[212:215], v[66:69]
	v_mfma_f32_16x16x32_bf16 v[70:73], v[172:175], v[216:219], v[70:73]
	v_mfma_f32_16x16x32_bf16 v[74:77], v[172:175], v[220:223], v[74:77]
	v_mfma_f32_16x16x32_bf16 v[78:81], v[172:175], v[224:227], v[78:81]
	v_mfma_f32_16x16x32_bf16 v[82:85], v[176:179], v[212:215], v[82:85]
	v_mfma_f32_16x16x32_bf16 v[86:89], v[176:179], v[216:219], v[86:89]
	v_mfma_f32_16x16x32_bf16 v[90:93], v[176:179], v[220:223], v[90:93]
	v_mfma_f32_16x16x32_bf16 v[94:97], v[176:179], v[224:227], v[94:97]
	v_mfma_f32_16x16x32_bf16 v[98:101], v[180:183], v[212:215], v[98:101]
	v_mfma_f32_16x16x32_bf16 v[102:105], v[180:183], v[216:219], v[102:105]
	v_mfma_f32_16x16x32_bf16 v[106:109], v[180:183], v[220:223], v[106:109]
	v_mfma_f32_16x16x32_bf16 v[110:113], v[180:183], v[224:227], v[110:113]
	v_mfma_f32_16x16x32_bf16 v[114:117], v[184:187], v[212:215], v[114:117]
	v_mfma_f32_16x16x32_bf16 v[118:121], v[184:187], v[216:219], v[118:121]
	v_mfma_f32_16x16x32_bf16 v[122:125], v[184:187], v[220:223], v[122:125]
	v_mfma_f32_16x16x32_bf16 v[126:129], v[184:187], v[224:227], v[126:129]
	s_nop 7
	s_barrier
	s_load_dwordx2 s[58:59], s[12:13], 0x100
	v_lshrrev_b32_e32 v241, 5, v131
	v_and_b32_e32 v242, 31, v131
	v_lshlrev_b32_e32 v243, 4, v242
	s_movk_i32 s56, 0x210
	v_mad_u32_u24 v239, v241, s56, v243
	v_add_u32_e32 v239, 16, v239
	v_lshlrev_b32_e32 v240, 13, v241
	v_or_b32_e32 v240, v240, v243
	s_lshl_b32 s56, s53, 13
	s_lshl_b32 s57, s54, 2
	s_add_i32 s56, s56, s57
	s_waitcnt lgkmcnt(0)
	s_add_u32 s58, s58, s56
	s_addc_u32 s59, s59, 0
	ds_write_b32 v238, v2
	ds_write_b32 v238, v3 offset:528
	ds_write_b32 v238, v4 offset:1056
	ds_write_b32 v238, v5 offset:1584
	ds_write_b32 v238, v6 offset:64
	ds_write_b32 v238, v7 offset:592
	ds_write_b32 v238, v8 offset:1120
	ds_write_b32 v238, v9 offset:1648
	ds_write_b32 v238, v10 offset:128
	ds_write_b32 v238, v11 offset:656
	ds_write_b32 v238, v12 offset:1184
	ds_write_b32 v238, v13 offset:1712
	ds_write_b32 v238, v14 offset:192
	ds_write_b32 v238, v15 offset:720
	ds_write_b32 v238, v16 offset:1248
	ds_write_b32 v238, v17 offset:1776
	ds_write_b32 v238, v18 offset:8448
	ds_write_b32 v238, v19 offset:8976
	ds_write_b32 v238, v20 offset:9504
	ds_write_b32 v238, v21 offset:10032
	ds_write_b32 v238, v22 offset:8512
	ds_write_b32 v238, v23 offset:9040
	ds_write_b32 v238, v24 offset:9568
	ds_write_b32 v238, v25 offset:10096
	ds_write_b32 v238, v26 offset:8576
	ds_write_b32 v238, v27 offset:9104
	ds_write_b32 v238, v28 offset:9632
	ds_write_b32 v238, v29 offset:10160
	ds_write_b32 v238, v30 offset:8640
	ds_write_b32 v238, v31 offset:9168
	ds_write_b32 v238, v32 offset:9696
	ds_write_b32 v238, v33 offset:10224
	ds_write_b32 v238, v34 offset:16896
	ds_write_b32 v238, v35 offset:17424
	ds_write_b32 v238, v36 offset:17952
	ds_write_b32 v238, v37 offset:18480
	ds_write_b32 v238, v38 offset:16960
	ds_write_b32 v238, v39 offset:17488
	ds_write_b32 v238, v40 offset:18016
	ds_write_b32 v238, v41 offset:18544
	ds_write_b32 v238, v42 offset:17024
	ds_write_b32 v238, v43 offset:17552
	ds_write_b32 v238, v44 offset:18080
	ds_write_b32 v238, v45 offset:18608
	ds_write_b32 v238, v46 offset:17088
	ds_write_b32 v238, v47 offset:17616
	ds_write_b32 v238, v48 offset:18144
	ds_write_b32 v238, v49 offset:18672
	ds_write_b32 v238, v50 offset:25344
	ds_write_b32 v238, v51 offset:25872
	ds_write_b32 v238, v52 offset:26400
	ds_write_b32 v238, v53 offset:26928
	ds_write_b32 v238, v54 offset:25408
	ds_write_b32 v238, v55 offset:25936
	ds_write_b32 v238, v56 offset:26464
	ds_write_b32 v238, v57 offset:26992
	ds_write_b32 v238, v58 offset:25472
	ds_write_b32 v238, v59 offset:26000
	ds_write_b32 v238, v60 offset:26528
	ds_write_b32 v238, v61 offset:27056
	ds_write_b32 v238, v62 offset:25536
	ds_write_b32 v238, v63 offset:26064
	ds_write_b32 v238, v64 offset:26592
	ds_write_b32 v238, v65 offset:27120
	s_mov_b32 s0, s58
	s_mov_b32 s1, s59
	global_load_dwordx4 v[136:139], v240, s[0:1]
	s_add_u32 s0, s0, 0x10000
	s_addc_u32 s1, s1, 0
	global_load_dwordx4 v[140:143], v240, s[0:1]
	s_add_u32 s0, s0, 0x10000
	s_addc_u32 s1, s1, 0
	global_load_dwordx4 v[144:147], v240, s[0:1]
	s_add_u32 s0, s0, 0x10000
	s_addc_u32 s1, s1, 0
	global_load_dwordx4 v[148:151], v240, s[0:1]
	s_add_u32 s0, s0, 0x10000
	s_addc_u32 s1, s1, 0
	global_load_dwordx4 v[172:175], v240, s[0:1]
	s_add_u32 s0, s0, 0x10000
	s_addc_u32 s1, s1, 0
	global_load_dwordx4 v[176:179], v240, s[0:1]
	s_add_u32 s0, s0, 0x10000
	s_addc_u32 s1, s1, 0
	global_load_dwordx4 v[180:183], v240, s[0:1]
	s_add_u32 s0, s0, 0x10000
	s_addc_u32 s1, s1, 0
	global_load_dwordx4 v[184:187], v240, s[0:1]
	s_add_u32 s0, s0, 0x10000
	s_addc_u32 s1, s1, 0
	global_load_dwordx4 v[188:191], v240, s[0:1]
	s_add_u32 s0, s0, 0x10000
	s_addc_u32 s1, s1, 0
	global_load_dwordx4 v[196:199], v240, s[0:1]
	s_add_u32 s0, s0, 0x10000
	s_addc_u32 s1, s1, 0
	global_load_dwordx4 v[200:203], v240, s[0:1]
	s_add_u32 s0, s0, 0x10000
	s_addc_u32 s1, s1, 0
	global_load_dwordx4 v[204:207], v240, s[0:1]
	s_add_u32 s0, s0, 0x10000
	s_addc_u32 s1, s1, 0
	global_load_dwordx4 v[212:215], v240, s[0:1]
	s_add_u32 s0, s0, 0x10000
	s_addc_u32 s1, s1, 0
	global_load_dwordx4 v[216:219], v240, s[0:1]
	s_add_u32 s0, s0, 0x10000
	s_addc_u32 s1, s1, 0
	global_load_dwordx4 v[220:223], v240, s[0:1]
	s_add_u32 s0, s0, 0x10000
	s_addc_u32 s1, s1, 0
	global_load_dwordx4 v[224:227], v240, s[0:1]
	s_waitcnt lgkmcnt(0)
	s_barrier
	ds_read_b128 v[2:5], v239
	ds_read_b128 v[6:9], v239 offset:4224
	ds_read_b128 v[10:13], v239 offset:8448
	ds_read_b128 v[14:17], v239 offset:12672
	ds_read_b128 v[18:21], v239 offset:16896
	ds_read_b128 v[22:25], v239 offset:21120
	ds_read_b128 v[26:29], v239 offset:25344
	ds_read_b128 v[30:33], v239 offset:29568
	ds_read_b128 v[34:37], v239 offset:33792
	ds_read_b128 v[38:41], v239 offset:38016
	ds_read_b128 v[42:45], v239 offset:42240
	ds_read_b128 v[46:49], v239 offset:46464
	ds_read_b128 v[50:53], v239 offset:50688
	ds_read_b128 v[54:57], v239 offset:54912
	ds_read_b128 v[58:61], v239 offset:59136
	ds_read_b128 v[62:65], v239 offset:63360
	s_mov_b32 s0, s58
	s_mov_b32 s1, s59
	s_waitcnt vmcnt(15) lgkmcnt(15)
	v_pk_add_f32 v[2:3], v[2:3], v[136:137]
	v_pk_add_f32 v[4:5], v[4:5], v[138:139]
	s_waitcnt vmcnt(14) lgkmcnt(14)
	v_pk_add_f32 v[6:7], v[6:7], v[140:141]
	v_pk_add_f32 v[8:9], v[8:9], v[142:143]
	s_waitcnt vmcnt(13) lgkmcnt(13)
	v_pk_add_f32 v[10:11], v[10:11], v[144:145]
	v_pk_add_f32 v[12:13], v[12:13], v[146:147]
	s_waitcnt vmcnt(12) lgkmcnt(12)
	v_pk_add_f32 v[14:15], v[14:15], v[148:149]
	v_pk_add_f32 v[16:17], v[16:17], v[150:151]
	s_waitcnt vmcnt(11) lgkmcnt(11)
	v_pk_add_f32 v[18:19], v[18:19], v[172:173]
	v_pk_add_f32 v[20:21], v[20:21], v[174:175]
	s_waitcnt vmcnt(10) lgkmcnt(10)
	v_pk_add_f32 v[22:23], v[22:23], v[176:177]
	v_pk_add_f32 v[24:25], v[24:25], v[178:179]
	s_waitcnt vmcnt(9) lgkmcnt(9)
	v_pk_add_f32 v[26:27], v[26:27], v[180:181]
	v_pk_add_f32 v[28:29], v[28:29], v[182:183]
	s_waitcnt vmcnt(8) lgkmcnt(8)
	v_pk_add_f32 v[30:31], v[30:31], v[184:185]
	v_pk_add_f32 v[32:33], v[32:33], v[186:187]
	s_waitcnt vmcnt(7) lgkmcnt(7)
	v_pk_add_f32 v[34:35], v[34:35], v[188:189]
	v_pk_add_f32 v[36:37], v[36:37], v[190:191]
	s_waitcnt vmcnt(6) lgkmcnt(6)
	v_pk_add_f32 v[38:39], v[38:39], v[196:197]
	v_pk_add_f32 v[40:41], v[40:41], v[198:199]
	s_waitcnt vmcnt(5) lgkmcnt(5)
	v_pk_add_f32 v[42:43], v[42:43], v[200:201]
	v_pk_add_f32 v[44:45], v[44:45], v[202:203]
	s_waitcnt vmcnt(4) lgkmcnt(4)
	v_pk_add_f32 v[46:47], v[46:47], v[204:205]
	v_pk_add_f32 v[48:49], v[48:49], v[206:207]
	s_waitcnt vmcnt(3) lgkmcnt(3)
	v_pk_add_f32 v[50:51], v[50:51], v[212:213]
	v_pk_add_f32 v[52:53], v[52:53], v[214:215]
	s_waitcnt vmcnt(2) lgkmcnt(2)
	v_pk_add_f32 v[54:55], v[54:55], v[216:217]
	v_pk_add_f32 v[56:57], v[56:57], v[218:219]
	s_waitcnt vmcnt(1) lgkmcnt(1)
	v_pk_add_f32 v[58:59], v[58:59], v[220:221]
	v_pk_add_f32 v[60:61], v[60:61], v[222:223]
	s_waitcnt vmcnt(0) lgkmcnt(0)
	v_pk_add_f32 v[62:63], v[62:63], v[224:225]
	v_pk_add_f32 v[64:65], v[64:65], v[226:227]
	global_store_dwordx4 v240, v[2:5], s[0:1]
	s_add_u32 s0, s0, 0x10000
	s_addc_u32 s1, s1, 0
	global_store_dwordx4 v240, v[6:9], s[0:1]
	s_add_u32 s0, s0, 0x10000
	s_addc_u32 s1, s1, 0
	global_store_dwordx4 v240, v[10:13], s[0:1]
	s_add_u32 s0, s0, 0x10000
	s_addc_u32 s1, s1, 0
	global_store_dwordx4 v240, v[14:17], s[0:1]
	s_add_u32 s0, s0, 0x10000
	s_addc_u32 s1, s1, 0
	global_store_dwordx4 v240, v[18:21], s[0:1]
	s_add_u32 s0, s0, 0x10000
	s_addc_u32 s1, s1, 0
	global_store_dwordx4 v240, v[22:25], s[0:1]
	s_add_u32 s0, s0, 0x10000
	s_addc_u32 s1, s1, 0
	global_store_dwordx4 v240, v[26:29], s[0:1]
	s_add_u32 s0, s0, 0x10000
	s_addc_u32 s1, s1, 0
	global_store_dwordx4 v240, v[30:33], s[0:1]
	s_add_u32 s0, s0, 0x10000
	s_addc_u32 s1, s1, 0
	global_store_dwordx4 v240, v[34:37], s[0:1]
	s_add_u32 s0, s0, 0x10000
	s_addc_u32 s1, s1, 0
	global_store_dwordx4 v240, v[38:41], s[0:1]
	s_add_u32 s0, s0, 0x10000
	s_addc_u32 s1, s1, 0
	global_store_dwordx4 v240, v[42:45], s[0:1]
	s_add_u32 s0, s0, 0x10000
	s_addc_u32 s1, s1, 0
	global_store_dwordx4 v240, v[46:49], s[0:1]
	s_add_u32 s0, s0, 0x10000
	s_addc_u32 s1, s1, 0
	global_store_dwordx4 v240, v[50:53], s[0:1]
	s_add_u32 s0, s0, 0x10000
	s_addc_u32 s1, s1, 0
	global_store_dwordx4 v240, v[54:57], s[0:1]
	s_add_u32 s0, s0, 0x10000
	s_addc_u32 s1, s1, 0
	global_store_dwordx4 v240, v[58:61], s[0:1]
	s_add_u32 s0, s0, 0x10000
	s_addc_u32 s1, s1, 0
	global_store_dwordx4 v240, v[62:65], s[0:1]
	s_add_u32 s58, s58, 0x1000
	s_addc_u32 s59, s59, 0
	s_waitcnt lgkmcnt(0)
	s_barrier
	ds_write_b32 v238, v66
	ds_write_b32 v238, v67 offset:528
	ds_write_b32 v238, v68 offset:1056
	ds_write_b32 v238, v69 offset:1584
	ds_write_b32 v238, v70 offset:64
	ds_write_b32 v238, v71 offset:592
	ds_write_b32 v238, v72 offset:1120
	ds_write_b32 v238, v73 offset:1648
	ds_write_b32 v238, v74 offset:128
	ds_write_b32 v238, v75 offset:656
	ds_write_b32 v238, v76 offset:1184
	ds_write_b32 v238, v77 offset:1712
	ds_write_b32 v238, v78 offset:192
	ds_write_b32 v238, v79 offset:720
	ds_write_b32 v238, v80 offset:1248
	ds_write_b32 v238, v81 offset:1776
	ds_write_b32 v238, v82 offset:8448
	ds_write_b32 v238, v83 offset:8976
	ds_write_b32 v238, v84 offset:9504
	ds_write_b32 v238, v85 offset:10032
	ds_write_b32 v238, v86 offset:8512
	ds_write_b32 v238, v87 offset:9040
	ds_write_b32 v238, v88 offset:9568
	ds_write_b32 v238, v89 offset:10096
	ds_write_b32 v238, v90 offset:8576
	ds_write_b32 v238, v91 offset:9104
	ds_write_b32 v238, v92 offset:9632
	ds_write_b32 v238, v93 offset:10160
	ds_write_b32 v238, v94 offset:8640
	ds_write_b32 v238, v95 offset:9168
	ds_write_b32 v238, v96 offset:9696
	ds_write_b32 v238, v97 offset:10224
	ds_write_b32 v238, v98 offset:16896
	ds_write_b32 v238, v99 offset:17424
	ds_write_b32 v238, v100 offset:17952
	ds_write_b32 v238, v101 offset:18480
	ds_write_b32 v238, v102 offset:16960
	ds_write_b32 v238, v103 offset:17488
	ds_write_b32 v238, v104 offset:18016
	ds_write_b32 v238, v105 offset:18544
	ds_write_b32 v238, v106 offset:17024
	ds_write_b32 v238, v107 offset:17552
	ds_write_b32 v238, v108 offset:18080
	ds_write_b32 v238, v109 offset:18608
	ds_write_b32 v238, v110 offset:17088
	ds_write_b32 v238, v111 offset:17616
	ds_write_b32 v238, v112 offset:18144
	ds_write_b32 v238, v113 offset:18672
	ds_write_b32 v238, v114 offset:25344
	ds_write_b32 v238, v115 offset:25872
	ds_write_b32 v238, v116 offset:26400
	ds_write_b32 v238, v117 offset:26928
	ds_write_b32 v238, v118 offset:25408
	ds_write_b32 v238, v119 offset:25936
	ds_write_b32 v238, v120 offset:26464
	ds_write_b32 v238, v121 offset:26992
	ds_write_b32 v238, v122 offset:25472
	ds_write_b32 v238, v123 offset:26000
	ds_write_b32 v238, v124 offset:26528
	ds_write_b32 v238, v125 offset:27056
	ds_write_b32 v238, v126 offset:25536
	ds_write_b32 v238, v127 offset:26064
	ds_write_b32 v238, v128 offset:26592
	ds_write_b32 v238, v129 offset:27120
	s_mov_b32 s0, s58
	s_mov_b32 s1, s59
	global_load_dwordx4 v[136:139], v240, s[0:1]
	s_add_u32 s0, s0, 0x10000
	s_addc_u32 s1, s1, 0
	global_load_dwordx4 v[140:143], v240, s[0:1]
	s_add_u32 s0, s0, 0x10000
	s_addc_u32 s1, s1, 0
	global_load_dwordx4 v[144:147], v240, s[0:1]
	s_add_u32 s0, s0, 0x10000
	s_addc_u32 s1, s1, 0
	global_load_dwordx4 v[148:151], v240, s[0:1]
	s_add_u32 s0, s0, 0x10000
	s_addc_u32 s1, s1, 0
	global_load_dwordx4 v[172:175], v240, s[0:1]
	s_add_u32 s0, s0, 0x10000
	s_addc_u32 s1, s1, 0
	global_load_dwordx4 v[176:179], v240, s[0:1]
	s_add_u32 s0, s0, 0x10000
	s_addc_u32 s1, s1, 0
	global_load_dwordx4 v[180:183], v240, s[0:1]
	s_add_u32 s0, s0, 0x10000
	s_addc_u32 s1, s1, 0
	global_load_dwordx4 v[184:187], v240, s[0:1]
	s_add_u32 s0, s0, 0x10000
	s_addc_u32 s1, s1, 0
	global_load_dwordx4 v[188:191], v240, s[0:1]
	s_add_u32 s0, s0, 0x10000
	s_addc_u32 s1, s1, 0
	global_load_dwordx4 v[196:199], v240, s[0:1]
	s_add_u32 s0, s0, 0x10000
	s_addc_u32 s1, s1, 0
	global_load_dwordx4 v[200:203], v240, s[0:1]
	s_add_u32 s0, s0, 0x10000
	s_addc_u32 s1, s1, 0
	global_load_dwordx4 v[204:207], v240, s[0:1]
	s_add_u32 s0, s0, 0x10000
	s_addc_u32 s1, s1, 0
	global_load_dwordx4 v[212:215], v240, s[0:1]
	s_add_u32 s0, s0, 0x10000
	s_addc_u32 s1, s1, 0
	global_load_dwordx4 v[216:219], v240, s[0:1]
	s_add_u32 s0, s0, 0x10000
	s_addc_u32 s1, s1, 0
	global_load_dwordx4 v[220:223], v240, s[0:1]
	s_add_u32 s0, s0, 0x10000
	s_addc_u32 s1, s1, 0
	global_load_dwordx4 v[224:227], v240, s[0:1]
	s_waitcnt lgkmcnt(0)
	s_barrier
	ds_read_b128 v[66:69], v239
	ds_read_b128 v[70:73], v239 offset:4224
	ds_read_b128 v[74:77], v239 offset:8448
	ds_read_b128 v[78:81], v239 offset:12672
	ds_read_b128 v[82:85], v239 offset:16896
	ds_read_b128 v[86:89], v239 offset:21120
	ds_read_b128 v[90:93], v239 offset:25344
	ds_read_b128 v[94:97], v239 offset:29568
	ds_read_b128 v[98:101], v239 offset:33792
	ds_read_b128 v[102:105], v239 offset:38016
	ds_read_b128 v[106:109], v239 offset:42240
	ds_read_b128 v[110:113], v239 offset:46464
	ds_read_b128 v[114:117], v239 offset:50688
	ds_read_b128 v[118:121], v239 offset:54912
	ds_read_b128 v[122:125], v239 offset:59136
	ds_read_b128 v[126:129], v239 offset:63360
	s_mov_b32 s0, s58
	s_mov_b32 s1, s59
	s_waitcnt vmcnt(15) lgkmcnt(15)
	v_pk_add_f32 v[66:67], v[66:67], v[136:137]
	v_pk_add_f32 v[68:69], v[68:69], v[138:139]
	s_waitcnt vmcnt(14) lgkmcnt(14)
	v_pk_add_f32 v[70:71], v[70:71], v[140:141]
	v_pk_add_f32 v[72:73], v[72:73], v[142:143]
	s_waitcnt vmcnt(13) lgkmcnt(13)
	v_pk_add_f32 v[74:75], v[74:75], v[144:145]
	v_pk_add_f32 v[76:77], v[76:77], v[146:147]
	s_waitcnt vmcnt(12) lgkmcnt(12)
	v_pk_add_f32 v[78:79], v[78:79], v[148:149]
	v_pk_add_f32 v[80:81], v[80:81], v[150:151]
	s_waitcnt vmcnt(11) lgkmcnt(11)
	v_pk_add_f32 v[82:83], v[82:83], v[172:173]
	v_pk_add_f32 v[84:85], v[84:85], v[174:175]
	s_waitcnt vmcnt(10) lgkmcnt(10)
	v_pk_add_f32 v[86:87], v[86:87], v[176:177]
	v_pk_add_f32 v[88:89], v[88:89], v[178:179]
	s_waitcnt vmcnt(9) lgkmcnt(9)
	v_pk_add_f32 v[90:91], v[90:91], v[180:181]
	v_pk_add_f32 v[92:93], v[92:93], v[182:183]
	s_waitcnt vmcnt(8) lgkmcnt(8)
	v_pk_add_f32 v[94:95], v[94:95], v[184:185]
	v_pk_add_f32 v[96:97], v[96:97], v[186:187]
	s_waitcnt vmcnt(7) lgkmcnt(7)
	v_pk_add_f32 v[98:99], v[98:99], v[188:189]
	v_pk_add_f32 v[100:101], v[100:101], v[190:191]
	s_waitcnt vmcnt(6) lgkmcnt(6)
	v_pk_add_f32 v[102:103], v[102:103], v[196:197]
	v_pk_add_f32 v[104:105], v[104:105], v[198:199]
	s_waitcnt vmcnt(5) lgkmcnt(5)
	v_pk_add_f32 v[106:107], v[106:107], v[200:201]
	v_pk_add_f32 v[108:109], v[108:109], v[202:203]
	s_waitcnt vmcnt(4) lgkmcnt(4)
	v_pk_add_f32 v[110:111], v[110:111], v[204:205]
	v_pk_add_f32 v[112:113], v[112:113], v[206:207]
	s_waitcnt vmcnt(3) lgkmcnt(3)
	v_pk_add_f32 v[114:115], v[114:115], v[212:213]
	v_pk_add_f32 v[116:117], v[116:117], v[214:215]
	s_waitcnt vmcnt(2) lgkmcnt(2)
	v_pk_add_f32 v[118:119], v[118:119], v[216:217]
	v_pk_add_f32 v[120:121], v[120:121], v[218:219]
	s_waitcnt vmcnt(1) lgkmcnt(1)
	v_pk_add_f32 v[122:123], v[122:123], v[220:221]
	v_pk_add_f32 v[124:125], v[124:125], v[222:223]
	s_waitcnt vmcnt(0) lgkmcnt(0)
	v_pk_add_f32 v[126:127], v[126:127], v[224:225]
	v_pk_add_f32 v[128:129], v[128:129], v[226:227]
	global_store_dwordx4 v240, v[66:69], s[0:1]
	s_add_u32 s0, s0, 0x10000
	s_addc_u32 s1, s1, 0
	global_store_dwordx4 v240, v[70:73], s[0:1]
	s_add_u32 s0, s0, 0x10000
	s_addc_u32 s1, s1, 0
	global_store_dwordx4 v240, v[74:77], s[0:1]
	s_add_u32 s0, s0, 0x10000
	s_addc_u32 s1, s1, 0
	global_store_dwordx4 v240, v[78:81], s[0:1]
	s_add_u32 s0, s0, 0x10000
	s_addc_u32 s1, s1, 0
	global_store_dwordx4 v240, v[82:85], s[0:1]
	s_add_u32 s0, s0, 0x10000
	s_addc_u32 s1, s1, 0
	global_store_dwordx4 v240, v[86:89], s[0:1]
	s_add_u32 s0, s0, 0x10000
	s_addc_u32 s1, s1, 0
	global_store_dwordx4 v240, v[90:93], s[0:1]
	s_add_u32 s0, s0, 0x10000
	s_addc_u32 s1, s1, 0
	global_store_dwordx4 v240, v[94:97], s[0:1]
	s_add_u32 s0, s0, 0x10000
	s_addc_u32 s1, s1, 0
	global_store_dwordx4 v240, v[98:101], s[0:1]
	s_add_u32 s0, s0, 0x10000
	s_addc_u32 s1, s1, 0
	global_store_dwordx4 v240, v[102:105], s[0:1]
	s_add_u32 s0, s0, 0x10000
	s_addc_u32 s1, s1, 0
	global_store_dwordx4 v240, v[106:109], s[0:1]
	s_add_u32 s0, s0, 0x10000
	s_addc_u32 s1, s1, 0
	global_store_dwordx4 v240, v[110:113], s[0:1]
	s_add_u32 s0, s0, 0x10000
	s_addc_u32 s1, s1, 0
	global_store_dwordx4 v240, v[114:117], s[0:1]
	s_add_u32 s0, s0, 0x10000
	s_addc_u32 s1, s1, 0
	global_store_dwordx4 v240, v[118:121], s[0:1]
	s_add_u32 s0, s0, 0x10000
	s_addc_u32 s1, s1, 0
	global_store_dwordx4 v240, v[122:125], s[0:1]
	s_add_u32 s0, s0, 0x10000
	s_addc_u32 s1, s1, 0
	global_store_dwordx4 v240, v[126:129], s[0:1]
	s_add_i32 s21, s21, s72
	s_cmpk_lt_i32 s21, 0x200
	s_waitcnt lgkmcnt(0)
	s_barrier
	s_cbranch_scc1 .Lfin3_tile
.Lfin3_done:
.LBB0_88:
	s_mov_b64 s[40:41], 0

.Lgu2_vloop:
	s_mov_b32 s55, 0
.Lgu2_tile:
	s_load_dwordx2 s[44:45], s[12:13], 0x160
	s_load_dwordx2 s[46:47], s[12:13], 0x130
	s_bfe_u32 s53, s21, 0x30006
	s_lshl_b32 s53, s53, 3
	s_and_b32 s56, s21, 7
	s_or_b32 s53, s53, s56
	s_lshl_b32 s53, s53, 7
	s_bfe_u32 s54, s21, 0x30003
	s_lshl_b32 s56, s55, 4
	s_add_i32 s54, s54, s56
	s_lshl_b32 s54, s54, 7
	v_lshrrev_b32_e32 v241, 6, v131
	v_and_b32_e32 v242, 63, v131
	s_nop 0
	v_readfirstlane_b32 s50, v241
	v_lshrrev_b32_e32 v241, 3, v242
	v_lshrrev_b32_e32 v243, 4, v242
	v_and_b32_e32 v244, 7, v242
	s_movk_i32 s56, 0x1080
	v_xor_b32_e32 v245, v244, v243
	v_lshlrev_b32_e32 v245, 4, v245
	v_mad_u32_u24 v228, v241, s56, v245
	v_or_b32_e32 v243, 4, v243
	v_xor_b32_e32 v245, v244, v243
	v_lshlrev_b32_e32 v245, 4, v245
	v_add_u32_e32 v241, 8, v241
	v_mad_u32_u24 v230, v241, s56, v245
	v_add_u32_e32 v229, 0x42000, v228
	v_add_u32_e32 v231, 0x42000, v230
	v_and_b32_e32 v241, 15, v242
	v_lshrrev_b32_e32 v243, 4, v242
	v_bfe_u32 v244, v242, 1, 3
	v_xor_b32_e32 v244, v243, v244
	v_lshlrev_b32_e32 v244, 4, v244
	v_lshl_or_b32 v232, v241, 7, v244
	v_xor_b32_e32 v233, 64, v232
	s_lshr_b32 s56, s50, 1
	s_and_b32 s57, s50, 1
	s_mul_i32 s0, s56, 64*528
	s_lshl_b32 s52, s57, 8
	s_add_i32 s0, s0, s52
	s_add_i32 s0, s0, 16
	v_mul_u32_u24_e32 v243, 4*528, v243
	v_lshl_add_u32 v243, v241, 2, v243
	v_add_u32_e32 v238, s0, v243
	s_add_i32 s22, s56, 0
	s_lshl_b32 s22, s22, 13
	s_add_i32 s22, s22, 16
	s_add_i32 s28, s57, 2
	s_lshl_b32 s28, s28, 13
	s_add_i32 s28, s28, 16
	s_add_i32 s40, s57, 4
	s_lshl_b32 s40, s40, 13
	s_add_i32 s40, s40, 16
	s_add_i32 s23, s56, 6
	s_lshl_b32 s23, s23, 13
	s_add_i32 s23, s23, 16
	s_add_i32 s29, s57, 8
	s_cmp_ge_u32 s29, 9
	s_cselect_b32 s0, 9, 0
	s_sub_i32 s29, s29, s0
	s_lshl_b32 s29, s29, 13
	s_add_i32 s29, s29, 16
	s_add_i32 s41, s57, 1
	s_lshl_b32 s41, s41, 13
	s_add_i32 s41, s41, 16
	s_add_i32 s24, s56, 3
	s_lshl_b32 s24, s24, 13
	s_add_i32 s24, s24, 16
	s_add_i32 s30, s57, 5
	s_lshl_b32 s30, s30, 13
	s_add_i32 s30, s30, 16
	s_add_i32 s42, s57, 7
	s_lshl_b32 s42, s42, 13
	s_add_i32 s42, s42, 16
	s_lshl_b32 s56, s50, 4
	s_add_i32 s57, s53, s56
	s_add_i32 s56, s54, s56
	s_mul_i32 s57, s57, 0x1080
	s_mul_i32 s56, s56, 0x1080
	s_waitcnt lgkmcnt(0)
	s_add_u32 s44, s44, s57
	s_addc_u32 s45, s45, 0
	s_add_u32 s46, s46, s56
	s_addc_u32 s47, s47, 0
	s_add_u32 s48, s46, 0x420000
	s_addc_u32 s49, s47, 0
	s_lshl_b32 s51, s50, 11
	s_add_i32 s51, s51, 16
	v_mov_b32_e32 v2, 0
	v_mov_b32_e32 v3, 0
	v_mov_b32_e32 v4, 0
	v_mov_b32_e32 v5, 0
	v_mov_b32_e32 v6, 0
	v_mov_b32_e32 v7, 0
	v_mov_b32_e32 v8, 0
	v_mov_b32_e32 v9, 0
	v_mov_b32_e32 v10, 0
	v_mov_b32_e32 v11, 0
	v_mov_b32_e32 v12, 0
	v_mov_b32_e32 v13, 0
	v_mov_b32_e32 v14, 0
	v_mov_b32_e32 v15, 0
	v_mov_b32_e32 v16, 0
	v_mov_b32_e32 v17, 0
	v_mov_b32_e32 v18, 0
	v_mov_b32_e32 v19, 0
	v_mov_b32_e32 v20, 0
	v_mov_b32_e32 v21, 0
	v_mov_b32_e32 v22, 0
	v_mov_b32_e32 v23, 0
	v_mov_b32_e32 v24, 0
	v_mov_b32_e32 v25, 0
	v_mov_b32_e32 v26, 0
	v_mov_b32_e32 v27, 0
	v_mov_b32_e32 v28, 0
	v_mov_b32_e32 v29, 0
	v_mov_b32_e32 v30, 0
	v_mov_b32_e32 v31, 0
	v_mov_b32_e32 v32, 0
	v_mov_b32_e32 v33, 0
	v_mov_b32_e32 v34, 0
	v_mov_b32_e32 v35, 0
	v_mov_b32_e32 v36, 0
	v_mov_b32_e32 v37, 0
	v_mov_b32_e32 v38, 0
	v_mov_b32_e32 v39, 0
	v_mov_b32_e32 v40, 0
	v_mov_b32_e32 v41, 0
	v_mov_b32_e32 v42, 0
	v_mov_b32_e32 v43, 0
	v_mov_b32_e32 v44, 0
	v_mov_b32_e32 v45, 0
	v_mov_b32_e32 v46, 0
	v_mov_b32_e32 v47, 0
	v_mov_b32_e32 v48, 0
	v_mov_b32_e32 v49, 0
	v_mov_b32_e32 v50, 0
	v_mov_b32_e32 v51, 0
	v_mov_b32_e32 v52, 0
	v_mov_b32_e32 v53, 0
	v_mov_b32_e32 v54, 0
	v_mov_b32_e32 v55, 0
	v_mov_b32_e32 v56, 0
	v_mov_b32_e32 v57, 0
	v_mov_b32_e32 v58, 0
	v_mov_b32_e32 v59, 0
	v_mov_b32_e32 v60, 0
	v_mov_b32_e32 v61, 0
	v_mov_b32_e32 v62, 0
	v_mov_b32_e32 v63, 0
	v_mov_b32_e32 v64, 0
	v_mov_b32_e32 v65, 0
	v_mov_b32_e32 v66, 0
	v_mov_b32_e32 v67, 0
	v_mov_b32_e32 v68, 0
	v_mov_b32_e32 v69, 0
	v_mov_b32_e32 v70, 0
	v_mov_b32_e32 v71, 0
	v_mov_b32_e32 v72, 0
	v_mov_b32_e32 v73, 0
	v_mov_b32_e32 v74, 0
	v_mov_b32_e32 v75, 0
	v_mov_b32_e32 v76, 0
	v_mov_b32_e32 v77, 0
	v_mov_b32_e32 v78, 0
	v_mov_b32_e32 v79, 0
	v_mov_b32_e32 v80, 0
	v_mov_b32_e32 v81, 0
	v_mov_b32_e32 v82, 0
	v_mov_b32_e32 v83, 0
	v_mov_b32_e32 v84, 0
	v_mov_b32_e32 v85, 0
	v_mov_b32_e32 v86, 0
	v_mov_b32_e32 v87, 0
	v_mov_b32_e32 v88, 0
	v_mov_b32_e32 v89, 0
	v_mov_b32_e32 v90, 0
	v_mov_b32_e32 v91, 0
	v_mov_b32_e32 v92, 0
	v_mov_b32_e32 v93, 0
	v_mov_b32_e32 v94, 0
	v_mov_b32_e32 v95, 0
	v_mov_b32_e32 v96, 0
	v_mov_b32_e32 v97, 0
	v_mov_b32_e32 v98, 0
	v_mov_b32_e32 v99, 0
	v_mov_b32_e32 v100, 0
	v_mov_b32_e32 v101, 0
	v_mov_b32_e32 v102, 0
	v_mov_b32_e32 v103, 0
	v_mov_b32_e32 v104, 0
	v_mov_b32_e32 v105, 0
	v_mov_b32_e32 v106, 0
	v_mov_b32_e32 v107, 0
	v_mov_b32_e32 v108, 0
	v_mov_b32_e32 v109, 0
	v_mov_b32_e32 v110, 0
	v_mov_b32_e32 v111, 0
	v_mov_b32_e32 v112, 0
	v_mov_b32_e32 v113, 0
	v_mov_b32_e32 v114, 0
	v_mov_b32_e32 v115, 0
	v_mov_b32_e32 v116, 0
	v_mov_b32_e32 v117, 0
	v_mov_b32_e32 v118, 0
	v_mov_b32_e32 v119, 0
	v_mov_b32_e32 v120, 0
	v_mov_b32_e32 v121, 0
	v_mov_b32_e32 v122, 0
	v_mov_b32_e32 v123, 0
	v_mov_b32_e32 v124, 0
	v_mov_b32_e32 v125, 0
	v_mov_b32_e32 v126, 0
	v_mov_b32_e32 v127, 0
	v_mov_b32_e32 v128, 0
	v_mov_b32_e32 v129, 0
	s_load_dwordx2 s[56:57], s[12:13], 0x1d0
	v_lshrrev_b32_e32 v241, 4, v242
	s_lshr_b32 s0, s50, 1
	s_lshl_b32 s0, s0, 6
	s_add_i32 s0, s0, s53
	s_lshl_b32 s0, s0, 2
	v_lshlrev_b32_e32 v241, 4, v241
	s_waitcnt lgkmcnt(0)
	s_add_u32 s56, s56, s0
	s_addc_u32 s57, s57, 0
	global_load_dwordx4 v[152:155], v241, s[56:57]
	global_load_dwordx4 v[244:247], v241, s[56:57] offset:64
	global_load_dwordx4 v[248:251], v241, s[56:57] offset:128
	global_load_dwordx4 v[252:255], v241, s[56:57] offset:192
	s_barrier
	s_mov_b32 m0, s51
	s_nop 0
	global_load_lds_dwordx4 v228, s[44:45]
	s_add_i32 m0, s51, 0x400
	s_nop 0
	global_load_lds_dwordx4 v230, s[44:45]
	s_add_i32 m0, s51, 0x2000
	s_nop 0
	global_load_lds_dwordx4 v229, s[44:45]
	s_add_i32 m0, s51, 0x2400
	s_nop 0
	global_load_lds_dwordx4 v231, s[44:45]
	s_add_i32 m0, s51, 0x4000
	s_nop 0
	global_load_lds_dwordx4 v228, s[46:47]
	s_add_i32 m0, s51, 0x4400
	s_nop 0
	global_load_lds_dwordx4 v230, s[46:47]
	s_add_i32 m0, s51, 0x6000
	s_nop 0
	global_load_lds_dwordx4 v229, s[46:47]
	s_add_i32 m0, s51, 0x6400
	s_nop 0
	global_load_lds_dwordx4 v231, s[46:47]
	s_add_i32 m0, s51, 0x8000
	s_nop 0
	global_load_lds_dwordx4 v228, s[48:49]
	s_add_i32 m0, s51, 0x8400
	s_nop 0
	global_load_lds_dwordx4 v230, s[48:49]
	s_add_i32 m0, s51, 0xa000
	s_nop 0
	global_load_lds_dwordx4 v229, s[48:49]
	s_add_i32 m0, s51, 0xa400
	s_nop 0
	global_load_lds_dwordx4 v231, s[48:49]
	v_add_u32_e32 v228, 0x80, v228
	v_add_u32_e32 v229, 0x80, v229
	v_add_u32_e32 v230, 0x80, v230
	v_add_u32_e32 v231, 0x80, v231
	s_waitcnt vmcnt(4)
	s_barrier
	s_mov_b32 s52, 0
.Lgu2_loop:
	s_add_i32 m0, s51, 0xc000
	s_nop 0
	global_load_lds_dwordx4 v228, s[44:45]
	s_add_i32 m0, s51, 0xc400
	s_nop 0
	global_load_lds_dwordx4 v230, s[44:45]
	s_add_i32 m0, s51, 0xe000
	s_nop 0
	global_load_lds_dwordx4 v229, s[44:45]
	s_add_i32 m0, s51, 0xe400
	s_nop 0
	global_load_lds_dwordx4 v231, s[44:45]
	s_add_i32 m0, s51, 0x10000
	s_nop 0
	global_load_lds_dwordx4 v228, s[46:47]
	s_add_i32 m0, s51, 0x10400
	s_nop 0
	global_load_lds_dwordx4 v230, s[46:47]
	v_add_u32_e32 v234, s22, v232
	v_add_u32_e32 v236, s28, v232
	v_add_u32_e32 v235, s22, v233
	v_add_u32_e32 v237, s28, v233
	ds_read_b128 v[136:139], v234
	ds_read_b128 v[140:143], v234 offset:2048
	ds_read_b128 v[144:147], v234 offset:4096
	ds_read_b128 v[148:151], v234 offset:6144
	ds_read_b128 v[188:191], v236
	ds_read_b128 v[196:199], v236 offset:2048
	ds_read_b128 v[200:203], v236 offset:4096
	ds_read_b128 v[204:207], v236 offset:6144
	ds_read_b128 v[172:175], v235
	ds_read_b128 v[176:179], v235 offset:2048
	ds_read_b128 v[180:183], v235 offset:4096
	ds_read_b128 v[184:187], v235 offset:6144
	ds_read_b128 v[212:215], v237
	ds_read_b128 v[216:219], v237 offset:2048
	ds_read_b128 v[220:223], v237 offset:4096
	ds_read_b128 v[224:227], v237 offset:6144
	s_waitcnt lgkmcnt(8)
	v_mfma_f32_16x16x32_bf16 v[2:5], v[136:139], v[188:191], v[2:5]
	v_mfma_f32_16x16x32_bf16 v[6:9], v[136:139], v[196:199], v[6:9]
	v_mfma_f32_16x16x32_bf16 v[10:13], v[136:139], v[200:203], v[10:13]
	v_mfma_f32_16x16x32_bf16 v[14:17], v[136:139], v[204:207], v[14:17]
	v_mfma_f32_16x16x32_bf16 v[18:21], v[140:143], v[188:191], v[18:21]
	v_mfma_f32_16x16x32_bf16 v[22:25], v[140:143], v[196:199], v[22:25]
	v_mfma_f32_16x16x32_bf16 v[26:29], v[140:143], v[200:203], v[26:29]
	v_mfma_f32_16x16x32_bf16 v[30:33], v[140:143], v[204:207], v[30:33]
	v_mfma_f32_16x16x32_bf16 v[34:37], v[144:147], v[188:191], v[34:37]
	v_mfma_f32_16x16x32_bf16 v[38:41], v[144:147], v[196:199], v[38:41]
	v_mfma_f32_16x16x32_bf16 v[42:45], v[144:147], v[200:203], v[42:45]
	v_mfma_f32_16x16x32_bf16 v[46:49], v[144:147], v[204:207], v[46:49]
	v_mfma_f32_16x16x32_bf16 v[50:53], v[148:151], v[188:191], v[50:53]
	v_mfma_f32_16x16x32_bf16 v[54:57], v[148:151], v[196:199], v[54:57]
	v_mfma_f32_16x16x32_bf16 v[58:61], v[148:151], v[200:203], v[58:61]
	v_mfma_f32_16x16x32_bf16 v[62:65], v[148:151], v[204:207], v[62:65]
	s_waitcnt lgkmcnt(0)
	v_mfma_f32_16x16x32_bf16 v[2:5], v[172:175], v[212:215], v[2:5]
	v_mfma_f32_16x16x32_bf16 v[6:9], v[172:175], v[216:219], v[6:9]
	v_mfma_f32_16x16x32_bf16 v[10:13], v[172:175], v[220:223], v[10:13]
	v_mfma_f32_16x16x32_bf16 v[14:17], v[172:175], v[224:227], v[14:17]
	v_mfma_f32_16x16x32_bf16 v[18:21], v[176:179], v[212:215], v[18:21]
	v_mfma_f32_16x16x32_bf16 v[22:25], v[176:179], v[216:219], v[22:25]
	v_mfma_f32_16x16x32_bf16 v[26:29], v[176:179], v[220:223], v[26:29]
	v_mfma_f32_16x16x32_bf16 v[30:33], v[176:179], v[224:227], v[30:33]
	v_mfma_f32_16x16x32_bf16 v[34:37], v[180:183], v[212:215], v[34:37]
	v_mfma_f32_16x16x32_bf16 v[38:41], v[180:183], v[216:219], v[38:41]
	v_mfma_f32_16x16x32_bf16 v[42:45], v[180:183], v[220:223], v[42:45]
	v_mfma_f32_16x16x32_bf16 v[46:49], v[180:183], v[224:227], v[46:49]
	v_mfma_f32_16x16x32_bf16 v[50:53], v[184:187], v[212:215], v[50:53]
	v_mfma_f32_16x16x32_bf16 v[54:57], v[184:187], v[216:219], v[54:57]
	v_mfma_f32_16x16x32_bf16 v[58:61], v[184:187], v[220:223], v[58:61]
	v_mfma_f32_16x16x32_bf16 v[62:65], v[184:187], v[224:227], v[62:65]
	s_waitcnt vmcnt(6)
	s_barrier
	s_mov_b32 m0, s51
	s_nop 0
	global_load_lds_dwordx4 v229, s[46:47]
	s_add_i32 m0, s51, 0x400
	s_nop 0
	global_load_lds_dwordx4 v231, s[46:47]
	s_add_i32 m0, s51, 0x2000
	s_nop 0
	global_load_lds_dwordx4 v228, s[48:49]
	s_add_i32 m0, s51, 0x2400
	s_nop 0
	global_load_lds_dwordx4 v230, s[48:49]
	s_add_i32 m0, s51, 0x4000
	s_nop 0
	global_load_lds_dwordx4 v229, s[48:49]
	s_add_i32 m0, s51, 0x4400
	s_nop 0
	global_load_lds_dwordx4 v231, s[48:49]
	v_add_u32_e32 v236, s40, v232
	v_add_u32_e32 v237, s40, v233
	ds_read_b128 v[188:191], v236
	ds_read_b128 v[196:199], v236 offset:2048
	ds_read_b128 v[200:203], v236 offset:4096
	ds_read_b128 v[204:207], v236 offset:6144
	ds_read_b128 v[212:215], v237
	ds_read_b128 v[216:219], v237 offset:2048
	ds_read_b128 v[220:223], v237 offset:4096
	ds_read_b128 v[224:227], v237 offset:6144
	s_waitcnt lgkmcnt(4)
	v_mfma_f32_16x16x32_bf16 v[66:69], v[136:139], v[188:191], v[66:69]
	v_mfma_f32_16x16x32_bf16 v[70:73], v[136:139], v[196:199], v[70:73]
	v_mfma_f32_16x16x32_bf16 v[74:77], v[136:139], v[200:203], v[74:77]
	v_mfma_f32_16x16x32_bf16 v[78:81], v[136:139], v[204:207], v[78:81]
	v_mfma_f32_16x16x32_bf16 v[82:85], v[140:143], v[188:191], v[82:85]
	v_mfma_f32_16x16x32_bf16 v[86:89], v[140:143], v[196:199], v[86:89]
	v_mfma_f32_16x16x32_bf16 v[90:93], v[140:143], v[200:203], v[90:93]
	v_mfma_f32_16x16x32_bf16 v[94:97], v[140:143], v[204:207], v[94:97]
	v_mfma_f32_16x16x32_bf16 v[98:101], v[144:147], v[188:191], v[98:101]
	v_mfma_f32_16x16x32_bf16 v[102:105], v[144:147], v[196:199], v[102:105]
	v_mfma_f32_16x16x32_bf16 v[106:109], v[144:147], v[200:203], v[106:109]
	v_mfma_f32_16x16x32_bf16 v[110:113], v[144:147], v[204:207], v[110:113]
	v_mfma_f32_16x16x32_bf16 v[114:117], v[148:151], v[188:191], v[114:117]
	v_mfma_f32_16x16x32_bf16 v[118:121], v[148:151], v[196:199], v[118:121]
	v_mfma_f32_16x16x32_bf16 v[122:125], v[148:151], v[200:203], v[122:125]
	v_mfma_f32_16x16x32_bf16 v[126:129], v[148:151], v[204:207], v[126:129]
	s_waitcnt lgkmcnt(0)
	v_mfma_f32_16x16x32_bf16 v[66:69], v[172:175], v[212:215], v[66:69]
	v_mfma_f32_16x16x32_bf16 v[70:73], v[172:175], v[216:219], v[70:73]
	v_mfma_f32_16x16x32_bf16 v[74:77], v[172:175], v[220:223], v[74:77]
	v_mfma_f32_16x16x32_bf16 v[78:81], v[172:175], v[224:227], v[78:81]
	v_mfma_f32_16x16x32_bf16 v[82:85], v[176:179], v[212:215], v[82:85]
	v_mfma_f32_16x16x32_bf16 v[86:89], v[176:179], v[216:219], v[86:89]
	v_mfma_f32_16x16x32_bf16 v[90:93], v[176:179], v[220:223], v[90:93]
	v_mfma_f32_16x16x32_bf16 v[94:97], v[176:179], v[224:227], v[94:97]
	v_mfma_f32_16x16x32_bf16 v[98:101], v[180:183], v[212:215], v[98:101]
	v_mfma_f32_16x16x32_bf16 v[102:105], v[180:183], v[216:219], v[102:105]
	v_mfma_f32_16x16x32_bf16 v[106:109], v[180:183], v[220:223], v[106:109]
	v_mfma_f32_16x16x32_bf16 v[110:113], v[180:183], v[224:227], v[110:113]
	v_mfma_f32_16x16x32_bf16 v[114:117], v[184:187], v[212:215], v[114:117]
	v_mfma_f32_16x16x32_bf16 v[118:121], v[184:187], v[216:219], v[118:121]
	v_mfma_f32_16x16x32_bf16 v[122:125], v[184:187], v[220:223], v[122:125]
	v_mfma_f32_16x16x32_bf16 v[126:129], v[184:187], v[224:227], v[126:129]
	v_add_u32_e32 v228, 0x80, v228
	v_add_u32_e32 v229, 0x80, v229
	v_add_u32_e32 v230, 0x80, v230
	v_add_u32_e32 v231, 0x80, v231
	s_waitcnt vmcnt(4)
	s_barrier
	s_add_i32 m0, s51, 0x6000
	s_nop 0
	global_load_lds_dwordx4 v228, s[44:45]
	s_add_i32 m0, s51, 0x6400
	s_nop 0
	global_load_lds_dwordx4 v230, s[44:45]
	s_add_i32 m0, s51, 0x8000
	s_nop 0
	global_load_lds_dwordx4 v229, s[44:45]
	s_add_i32 m0, s51, 0x8400
	s_nop 0
	global_load_lds_dwordx4 v231, s[44:45]
	s_add_i32 m0, s51, 0xa000
	s_nop 0
	global_load_lds_dwordx4 v228, s[46:47]
	s_add_i32 m0, s51, 0xa400
	s_nop 0
	global_load_lds_dwordx4 v230, s[46:47]
	v_add_u32_e32 v234, s23, v232
	v_add_u32_e32 v236, s29, v232
	v_add_u32_e32 v235, s23, v233
	v_add_u32_e32 v237, s29, v233
	ds_read_b128 v[136:139], v234
	ds_read_b128 v[140:143], v234 offset:2048
	ds_read_b128 v[144:147], v234 offset:4096
	ds_read_b128 v[148:151], v234 offset:6144
	ds_read_b128 v[188:191], v236
	ds_read_b128 v[196:199], v236 offset:2048
	ds_read_b128 v[200:203], v236 offset:4096
	ds_read_b128 v[204:207], v236 offset:6144
	ds_read_b128 v[172:175], v235
	ds_read_b128 v[176:179], v235 offset:2048
	ds_read_b128 v[180:183], v235 offset:4096
	ds_read_b128 v[184:187], v235 offset:6144
	ds_read_b128 v[212:215], v237
	ds_read_b128 v[216:219], v237 offset:2048
	ds_read_b128 v[220:223], v237 offset:4096
	ds_read_b128 v[224:227], v237 offset:6144
	s_waitcnt lgkmcnt(8)
	v_mfma_f32_16x16x32_bf16 v[2:5], v[136:139], v[188:191], v[2:5]
	v_mfma_f32_16x16x32_bf16 v[6:9], v[136:139], v[196:199], v[6:9]
	v_mfma_f32_16x16x32_bf16 v[10:13], v[136:139], v[200:203], v[10:13]
	v_mfma_f32_16x16x32_bf16 v[14:17], v[136:139], v[204:207], v[14:17]
	v_mfma_f32_16x16x32_bf16 v[18:21], v[140:143], v[188:191], v[18:21]
	v_mfma_f32_16x16x32_bf16 v[22:25], v[140:143], v[196:199], v[22:25]
	v_mfma_f32_16x16x32_bf16 v[26:29], v[140:143], v[200:203], v[26:29]
	v_mfma_f32_16x16x32_bf16 v[30:33], v[140:143], v[204:207], v[30:33]
	v_mfma_f32_16x16x32_bf16 v[34:37], v[144:147], v[188:191], v[34:37]
	v_mfma_f32_16x16x32_bf16 v[38:41], v[144:147], v[196:199], v[38:41]
	v_mfma_f32_16x16x32_bf16 v[42:45], v[144:147], v[200:203], v[42:45]
	v_mfma_f32_16x16x32_bf16 v[46:49], v[144:147], v[204:207], v[46:49]
	v_mfma_f32_16x16x32_bf16 v[50:53], v[148:151], v[188:191], v[50:53]
	v_mfma_f32_16x16x32_bf16 v[54:57], v[148:151], v[196:199], v[54:57]
	v_mfma_f32_16x16x32_bf16 v[58:61], v[148:151], v[200:203], v[58:61]
	v_mfma_f32_16x16x32_bf16 v[62:65], v[148:151], v[204:207], v[62:65]
	s_waitcnt lgkmcnt(0)
	v_mfma_f32_16x16x32_bf16 v[2:5], v[172:175], v[212:215], v[2:5]
	v_mfma_f32_16x16x32_bf16 v[6:9], v[172:175], v[216:219], v[6:9]
	v_mfma_f32_16x16x32_bf16 v[10:13], v[172:175], v[220:223], v[10:13]
	v_mfma_f32_16x16x32_bf16 v[14:17], v[172:175], v[224:227], v[14:17]
	v_mfma_f32_16x16x32_bf16 v[18:21], v[176:179], v[212:215], v[18:21]
	v_mfma_f32_16x16x32_bf16 v[22:25], v[176:179], v[216:219], v[22:25]
	v_mfma_f32_16x16x32_bf16 v[26:29], v[176:179], v[220:223], v[26:29]
	v_mfma_f32_16x16x32_bf16 v[30:33], v[176:179], v[224:227], v[30:33]
	v_mfma_f32_16x16x32_bf16 v[34:37], v[180:183], v[212:215], v[34:37]
	v_mfma_f32_16x16x32_bf16 v[38:41], v[180:183], v[216:219], v[38:41]
	v_mfma_f32_16x16x32_bf16 v[42:45], v[180:183], v[220:223], v[42:45]
	v_mfma_f32_16x16x32_bf16 v[46:49], v[180:183], v[224:227], v[46:49]
	v_mfma_f32_16x16x32_bf16 v[50:53], v[184:187], v[212:215], v[50:53]
	v_mfma_f32_16x16x32_bf16 v[54:57], v[184:187], v[216:219], v[54:57]
	v_mfma_f32_16x16x32_bf16 v[58:61], v[184:187], v[220:223], v[58:61]
	v_mfma_f32_16x16x32_bf16 v[62:65], v[184:187], v[224:227], v[62:65]
	s_waitcnt vmcnt(6)
	s_barrier
	s_add_i32 m0, s51, 0xc000
	s_nop 0
	global_load_lds_dwordx4 v229, s[46:47]
	s_add_i32 m0, s51, 0xc400
	s_nop 0
	global_load_lds_dwordx4 v231, s[46:47]
	s_add_i32 m0, s51, 0xe000
	s_nop 0
	global_load_lds_dwordx4 v228, s[48:49]
	s_add_i32 m0, s51, 0xe400
	s_nop 0
	global_load_lds_dwordx4 v230, s[48:49]
	s_add_i32 m0, s51, 0x10000
	s_nop 0
	global_load_lds_dwordx4 v229, s[48:49]
	s_add_i32 m0, s51, 0x10400
	s_nop 0
	global_load_lds_dwordx4 v231, s[48:49]
	v_add_u32_e32 v236, s41, v232
	v_add_u32_e32 v237, s41, v233
	ds_read_b128 v[188:191], v236
	ds_read_b128 v[196:199], v236 offset:2048
	ds_read_b128 v[200:203], v236 offset:4096
	ds_read_b128 v[204:207], v236 offset:6144
	ds_read_b128 v[212:215], v237
	ds_read_b128 v[216:219], v237 offset:2048
	ds_read_b128 v[220:223], v237 offset:4096
	ds_read_b128 v[224:227], v237 offset:6144
	s_waitcnt lgkmcnt(4)
	v_mfma_f32_16x16x32_bf16 v[66:69], v[136:139], v[188:191], v[66:69]
	v_mfma_f32_16x16x32_bf16 v[70:73], v[136:139], v[196:199], v[70:73]
	v_mfma_f32_16x16x32_bf16 v[74:77], v[136:139], v[200:203], v[74:77]
	v_mfma_f32_16x16x32_bf16 v[78:81], v[136:139], v[204:207], v[78:81]
	v_mfma_f32_16x16x32_bf16 v[82:85], v[140:143], v[188:191], v[82:85]
	v_mfma_f32_16x16x32_bf16 v[86:89], v[140:143], v[196:199], v[86:89]
	v_mfma_f32_16x16x32_bf16 v[90:93], v[140:143], v[200:203], v[90:93]
	v_mfma_f32_16x16x32_bf16 v[94:97], v[140:143], v[204:207], v[94:97]
	v_mfma_f32_16x16x32_bf16 v[98:101], v[144:147], v[188:191], v[98:101]
	v_mfma_f32_16x16x32_bf16 v[102:105], v[144:147], v[196:199], v[102:105]
	v_mfma_f32_16x16x32_bf16 v[106:109], v[144:147], v[200:203], v[106:109]
	v_mfma_f32_16x16x32_bf16 v[110:113], v[144:147], v[204:207], v[110:113]
	v_mfma_f32_16x16x32_bf16 v[114:117], v[148:151], v[188:191], v[114:117]
	v_mfma_f32_16x16x32_bf16 v[118:121], v[148:151], v[196:199], v[118:121]
	v_mfma_f32_16x16x32_bf16 v[122:125], v[148:151], v[200:203], v[122:125]
	v_mfma_f32_16x16x32_bf16 v[126:129], v[148:151], v[204:207], v[126:129]
	s_waitcnt lgkmcnt(0)
	v_mfma_f32_16x16x32_bf16 v[66:69], v[172:175], v[212:215], v[66:69]
	v_mfma_f32_16x16x32_bf16 v[70:73], v[172:175], v[216:219], v[70:73]
	v_mfma_f32_16x16x32_bf16 v[74:77], v[172:175], v[220:223], v[74:77]
	v_mfma_f32_16x16x32_bf16 v[78:81], v[172:175], v[224:227], v[78:81]
	v_mfma_f32_16x16x32_bf16 v[82:85], v[176:179], v[212:215], v[82:85]
	v_mfma_f32_16x16x32_bf16 v[86:89], v[176:179], v[216:219], v[86:89]
	v_mfma_f32_16x16x32_bf16 v[90:93], v[176:179], v[220:223], v[90:93]
	v_mfma_f32_16x16x32_bf16 v[94:97], v[176:179], v[224:227], v[94:97]
	v_mfma_f32_16x16x32_bf16 v[98:101], v[180:183], v[212:215], v[98:101]
	v_mfma_f32_16x16x32_bf16 v[102:105], v[180:183], v[216:219], v[102:105]
	v_mfma_f32_16x16x32_bf16 v[106:109], v[180:183], v[220:223], v[106:109]
	v_mfma_f32_16x16x32_bf16 v[110:113], v[180:183], v[224:227], v[110:113]
	v_mfma_f32_16x16x32_bf16 v[114:117], v[184:187], v[212:215], v[114:117]
	v_mfma_f32_16x16x32_bf16 v[118:121], v[184:187], v[216:219], v[118:121]
	v_mfma_f32_16x16x32_bf16 v[122:125], v[184:187], v[220:223], v[122:125]
	v_mfma_f32_16x16x32_bf16 v[126:129], v[184:187], v[224:227], v[126:129]
	v_add_u32_e32 v228, 0x80, v228
	v_add_u32_e32 v229, 0x80, v229
	v_add_u32_e32 v230, 0x80, v230
	v_add_u32_e32 v231, 0x80, v231
	s_waitcnt vmcnt(4)
	s_barrier
	s_mov_b32 m0, s51
	s_nop 0
	global_load_lds_dwordx4 v228, s[44:45]
	s_add_i32 m0, s51, 0x400
	s_nop 0
	global_load_lds_dwordx4 v230, s[44:45]
	s_add_i32 m0, s51, 0x2000
	s_nop 0
	global_load_lds_dwordx4 v229, s[44:45]
	s_add_i32 m0, s51, 0x2400
	s_nop 0
	global_load_lds_dwordx4 v231, s[44:45]
	s_add_i32 m0, s51, 0x4000
	s_nop 0
	global_load_lds_dwordx4 v228, s[46:47]
	s_add_i32 m0, s51, 0x4400
	s_nop 0
	global_load_lds_dwordx4 v230, s[46:47]
	v_add_u32_e32 v234, s24, v232
	v_add_u32_e32 v236, s30, v232
	v_add_u32_e32 v235, s24, v233
	v_add_u32_e32 v237, s30, v233
	ds_read_b128 v[136:139], v234
	ds_read_b128 v[140:143], v234 offset:2048
	ds_read_b128 v[144:147], v234 offset:4096
	ds_read_b128 v[148:151], v234 offset:6144
	ds_read_b128 v[188:191], v236
	ds_read_b128 v[196:199], v236 offset:2048
	ds_read_b128 v[200:203], v236 offset:4096
	ds_read_b128 v[204:207], v236 offset:6144
	ds_read_b128 v[172:175], v235
	ds_read_b128 v[176:179], v235 offset:2048
	ds_read_b128 v[180:183], v235 offset:4096
	ds_read_b128 v[184:187], v235 offset:6144
	ds_read_b128 v[212:215], v237
	ds_read_b128 v[216:219], v237 offset:2048
	ds_read_b128 v[220:223], v237 offset:4096
	ds_read_b128 v[224:227], v237 offset:6144
	s_waitcnt lgkmcnt(8)
	v_mfma_f32_16x16x32_bf16 v[2:5], v[136:139], v[188:191], v[2:5]
	v_mfma_f32_16x16x32_bf16 v[6:9], v[136:139], v[196:199], v[6:9]
	v_mfma_f32_16x16x32_bf16 v[10:13], v[136:139], v[200:203], v[10:13]
	v_mfma_f32_16x16x32_bf16 v[14:17], v[136:139], v[204:207], v[14:17]
	v_mfma_f32_16x16x32_bf16 v[18:21], v[140:143], v[188:191], v[18:21]
	v_mfma_f32_16x16x32_bf16 v[22:25], v[140:143], v[196:199], v[22:25]
	v_mfma_f32_16x16x32_bf16 v[26:29], v[140:143], v[200:203], v[26:29]
	v_mfma_f32_16x16x32_bf16 v[30:33], v[140:143], v[204:207], v[30:33]
	v_mfma_f32_16x16x32_bf16 v[34:37], v[144:147], v[188:191], v[34:37]
	v_mfma_f32_16x16x32_bf16 v[38:41], v[144:147], v[196:199], v[38:41]
	v_mfma_f32_16x16x32_bf16 v[42:45], v[144:147], v[200:203], v[42:45]
	v_mfma_f32_16x16x32_bf16 v[46:49], v[144:147], v[204:207], v[46:49]
	v_mfma_f32_16x16x32_bf16 v[50:53], v[148:151], v[188:191], v[50:53]
	v_mfma_f32_16x16x32_bf16 v[54:57], v[148:151], v[196:199], v[54:57]
	v_mfma_f32_16x16x32_bf16 v[58:61], v[148:151], v[200:203], v[58:61]
	v_mfma_f32_16x16x32_bf16 v[62:65], v[148:151], v[204:207], v[62:65]
	s_waitcnt lgkmcnt(0)
	v_mfma_f32_16x16x32_bf16 v[2:5], v[172:175], v[212:215], v[2:5]
	v_mfma_f32_16x16x32_bf16 v[6:9], v[172:175], v[216:219], v[6:9]
	v_mfma_f32_16x16x32_bf16 v[10:13], v[172:175], v[220:223], v[10:13]
	v_mfma_f32_16x16x32_bf16 v[14:17], v[172:175], v[224:227], v[14:17]
	v_mfma_f32_16x16x32_bf16 v[18:21], v[176:179], v[212:215], v[18:21]
	v_mfma_f32_16x16x32_bf16 v[22:25], v[176:179], v[216:219], v[22:25]
	v_mfma_f32_16x16x32_bf16 v[26:29], v[176:179], v[220:223], v[26:29]
	v_mfma_f32_16x16x32_bf16 v[30:33], v[176:179], v[224:227], v[30:33]
	v_mfma_f32_16x16x32_bf16 v[34:37], v[180:183], v[212:215], v[34:37]
	v_mfma_f32_16x16x32_bf16 v[38:41], v[180:183], v[216:219], v[38:41]
	v_mfma_f32_16x16x32_bf16 v[42:45], v[180:183], v[220:223], v[42:45]
	v_mfma_f32_16x16x32_bf16 v[46:49], v[180:183], v[224:227], v[46:49]
	v_mfma_f32_16x16x32_bf16 v[50:53], v[184:187], v[212:215], v[50:53]
	v_mfma_f32_16x16x32_bf16 v[54:57], v[184:187], v[216:219], v[54:57]
	v_mfma_f32_16x16x32_bf16 v[58:61], v[184:187], v[220:223], v[58:61]
	v_mfma_f32_16x16x32_bf16 v[62:65], v[184:187], v[224:227], v[62:65]
	s_waitcnt vmcnt(6)
	s_barrier
	s_add_i32 m0, s51, 0x6000
	s_nop 0
	global_load_lds_dwordx4 v229, s[46:47]
	s_add_i32 m0, s51, 0x6400
	s_nop 0
	global_load_lds_dwordx4 v231, s[46:47]
	s_add_i32 m0, s51, 0x8000
	s_nop 0
	global_load_lds_dwordx4 v228, s[48:49]
	s_add_i32 m0, s51, 0x8400
	s_nop 0
	global_load_lds_dwordx4 v230, s[48:49]
	s_add_i32 m0, s51, 0xa000
	s_nop 0
	global_load_lds_dwordx4 v229, s[48:49]
	s_add_i32 m0, s51, 0xa400
	s_nop 0
	global_load_lds_dwordx4 v231, s[48:49]
	v_add_u32_e32 v236, s42, v232
	v_add_u32_e32 v237, s42, v233
	ds_read_b128 v[188:191], v236
	ds_read_b128 v[196:199], v236 offset:2048
	ds_read_b128 v[200:203], v236 offset:4096
	ds_read_b128 v[204:207], v236 offset:6144
	ds_read_b128 v[212:215], v237
	ds_read_b128 v[216:219], v237 offset:2048
	ds_read_b128 v[220:223], v237 offset:4096
	ds_read_b128 v[224:227], v237 offset:6144
	s_waitcnt lgkmcnt(4)
	v_mfma_f32_16x16x32_bf16 v[66:69], v[136:139], v[188:191], v[66:69]
	v_mfma_f32_16x16x32_bf16 v[70:73], v[136:139], v[196:199], v[70:73]
	v_mfma_f32_16x16x32_bf16 v[74:77], v[136:139], v[200:203], v[74:77]
	v_mfma_f32_16x16x32_bf16 v[78:81], v[136:139], v[204:207], v[78:81]
	v_mfma_f32_16x16x32_bf16 v[82:85], v[140:143], v[188:191], v[82:85]
	v_mfma_f32_16x16x32_bf16 v[86:89], v[140:143], v[196:199], v[86:89]
	v_mfma_f32_16x16x32_bf16 v[90:93], v[140:143], v[200:203], v[90:93]
	v_mfma_f32_16x16x32_bf16 v[94:97], v[140:143], v[204:207], v[94:97]
	v_mfma_f32_16x16x32_bf16 v[98:101], v[144:147], v[188:191], v[98:101]
	v_mfma_f32_16x16x32_bf16 v[102:105], v[144:147], v[196:199], v[102:105]
	v_mfma_f32_16x16x32_bf16 v[106:109], v[144:147], v[200:203], v[106:109]
	v_mfma_f32_16x16x32_bf16 v[110:113], v[144:147], v[204:207], v[110:113]
	v_mfma_f32_16x16x32_bf16 v[114:117], v[148:151], v[188:191], v[114:117]
	v_mfma_f32_16x16x32_bf16 v[118:121], v[148:151], v[196:199], v[118:121]
	v_mfma_f32_16x16x32_bf16 v[122:125], v[148:151], v[200:203], v[122:125]
	v_mfma_f32_16x16x32_bf16 v[126:129], v[148:151], v[204:207], v[126:129]
	s_waitcnt lgkmcnt(0)
	v_mfma_f32_16x16x32_bf16 v[66:69], v[172:175], v[212:215], v[66:69]
	v_mfma_f32_16x16x32_bf16 v[70:73], v[172:175], v[216:219], v[70:73]
	v_mfma_f32_16x16x32_bf16 v[74:77], v[172:175], v[220:223], v[74:77]
	v_mfma_f32_16x16x32_bf16 v[78:81], v[172:175], v[224:227], v[78:81]
	v_mfma_f32_16x16x32_bf16 v[82:85], v[176:179], v[212:215], v[82:85]
	v_mfma_f32_16x16x32_bf16 v[86:89], v[176:179], v[216:219], v[86:89]
	v_mfma_f32_16x16x32_bf16 v[90:93], v[176:179], v[220:223], v[90:93]
	v_mfma_f32_16x16x32_bf16 v[94:97], v[176:179], v[224:227], v[94:97]
	v_mfma_f32_16x16x32_bf16 v[98:101], v[180:183], v[212:215], v[98:101]
	v_mfma_f32_16x16x32_bf16 v[102:105], v[180:183], v[216:219], v[102:105]
	v_mfma_f32_16x16x32_bf16 v[106:109], v[180:183], v[220:223], v[106:109]
	v_mfma_f32_16x16x32_bf16 v[110:113], v[180:183], v[224:227], v[110:113]
	v_mfma_f32_16x16x32_bf16 v[114:117], v[184:187], v[212:215], v[114:117]
	v_mfma_f32_16x16x32_bf16 v[118:121], v[184:187], v[216:219], v[118:121]
	v_mfma_f32_16x16x32_bf16 v[122:125], v[184:187], v[220:223], v[122:125]
	v_mfma_f32_16x16x32_bf16 v[126:129], v[184:187], v[224:227], v[126:129]
	v_add_u32_e32 v228, 0x80, v228
	v_add_u32_e32 v229, 0x80, v229
	v_add_u32_e32 v230, 0x80, v230
	v_add_u32_e32 v231, 0x80, v231
	s_waitcnt vmcnt(4)
	s_barrier
	s_add_i32 s52, s52, 1
	s_cmp_lt_u32 s52, 10
	s_cbranch_scc1 .Lgu2_loop
	s_add_i32 m0, s51, 0xc000
	s_nop 0
	global_load_lds_dwordx4 v228, s[44:45]
	s_add_i32 m0, s51, 0xc400
	s_nop 0
	global_load_lds_dwordx4 v230, s[44:45]
	s_add_i32 m0, s51, 0xe000
	s_nop 0
	global_load_lds_dwordx4 v229, s[44:45]
	s_add_i32 m0, s51, 0xe400
	s_nop 0
	global_load_lds_dwordx4 v231, s[44:45]
	s_add_i32 m0, s51, 0x10000
	s_nop 0
	global_load_lds_dwordx4 v228, s[46:47]
	s_add_i32 m0, s51, 0x10400
	s_nop 0
	global_load_lds_dwordx4 v230, s[46:47]
	v_add_u32_e32 v234, s22, v232
	v_add_u32_e32 v236, s28, v232
	v_add_u32_e32 v235, s22, v233
	v_add_u32_e32 v237, s28, v233
	ds_read_b128 v[136:139], v234
	ds_read_b128 v[140:143], v234 offset:2048
	ds_read_b128 v[144:147], v234 offset:4096
	ds_read_b128 v[148:151], v234 offset:6144
	ds_read_b128 v[188:191], v236
	ds_read_b128 v[196:199], v236 offset:2048
	ds_read_b128 v[200:203], v236 offset:4096
	ds_read_b128 v[204:207], v236 offset:6144
	ds_read_b128 v[172:175], v235
	ds_read_b128 v[176:179], v235 offset:2048
	ds_read_b128 v[180:183], v235 offset:4096
	ds_read_b128 v[184:187], v235 offset:6144
	ds_read_b128 v[212:215], v237
	ds_read_b128 v[216:219], v237 offset:2048
	ds_read_b128 v[220:223], v237 offset:4096
	ds_read_b128 v[224:227], v237 offset:6144
	s_waitcnt lgkmcnt(8)
	v_mfma_f32_16x16x32_bf16 v[2:5], v[136:139], v[188:191], v[2:5]
	v_mfma_f32_16x16x32_bf16 v[6:9], v[136:139], v[196:199], v[6:9]
	v_mfma_f32_16x16x32_bf16 v[10:13], v[136:139], v[200:203], v[10:13]
	v_mfma_f32_16x16x32_bf16 v[14:17], v[136:139], v[204:207], v[14:17]
	v_mfma_f32_16x16x32_bf16 v[18:21], v[140:143], v[188:191], v[18:21]
	v_mfma_f32_16x16x32_bf16 v[22:25], v[140:143], v[196:199], v[22:25]
	v_mfma_f32_16x16x32_bf16 v[26:29], v[140:143], v[200:203], v[26:29]
	v_mfma_f32_16x16x32_bf16 v[30:33], v[140:143], v[204:207], v[30:33]
	v_mfma_f32_16x16x32_bf16 v[34:37], v[144:147], v[188:191], v[34:37]
	v_mfma_f32_16x16x32_bf16 v[38:41], v[144:147], v[196:199], v[38:41]
	v_mfma_f32_16x16x32_bf16 v[42:45], v[144:147], v[200:203], v[42:45]
	v_mfma_f32_16x16x32_bf16 v[46:49], v[144:147], v[204:207], v[46:49]
	v_mfma_f32_16x16x32_bf16 v[50:53], v[148:151], v[188:191], v[50:53]
	v_mfma_f32_16x16x32_bf16 v[54:57], v[148:151], v[196:199], v[54:57]
	v_mfma_f32_16x16x32_bf16 v[58:61], v[148:151], v[200:203], v[58:61]
	v_mfma_f32_16x16x32_bf16 v[62:65], v[148:151], v[204:207], v[62:65]
	s_waitcnt lgkmcnt(0)
	v_mfma_f32_16x16x32_bf16 v[2:5], v[172:175], v[212:215], v[2:5]
	v_mfma_f32_16x16x32_bf16 v[6:9], v[172:175], v[216:219], v[6:9]
	v_mfma_f32_16x16x32_bf16 v[10:13], v[172:175], v[220:223], v[10:13]
	v_mfma_f32_16x16x32_bf16 v[14:17], v[172:175], v[224:227], v[14:17]
	v_mfma_f32_16x16x32_bf16 v[18:21], v[176:179], v[212:215], v[18:21]
	v_mfma_f32_16x16x32_bf16 v[22:25], v[176:179], v[216:219], v[22:25]
	v_mfma_f32_16x16x32_bf16 v[26:29], v[176:179], v[220:223], v[26:29]
	v_mfma_f32_16x16x32_bf16 v[30:33], v[176:179], v[224:227], v[30:33]
	v_mfma_f32_16x16x32_bf16 v[34:37], v[180:183], v[212:215], v[34:37]
	v_mfma_f32_16x16x32_bf16 v[38:41], v[180:183], v[216:219], v[38:41]
	v_mfma_f32_16x16x32_bf16 v[42:45], v[180:183], v[220:223], v[42:45]
	v_mfma_f32_16x16x32_bf16 v[46:49], v[180:183], v[224:227], v[46:49]
	v_mfma_f32_16x16x32_bf16 v[50:53], v[184:187], v[212:215], v[50:53]
	v_mfma_f32_16x16x32_bf16 v[54:57], v[184:187], v[216:219], v[54:57]
	v_mfma_f32_16x16x32_bf16 v[58:61], v[184:187], v[220:223], v[58:61]
	v_mfma_f32_16x16x32_bf16 v[62:65], v[184:187], v[224:227], v[62:65]
	s_waitcnt vmcnt(6)
	s_barrier
	s_mov_b32 m0, s51
	s_nop 0
	global_load_lds_dwordx4 v229, s[46:47]
	s_add_i32 m0, s51, 0x400
	s_nop 0
	global_load_lds_dwordx4 v231, s[46:47]
	s_add_i32 m0, s51, 0x2000
	s_nop 0
	global_load_lds_dwordx4 v228, s[48:49]
	s_add_i32 m0, s51, 0x2400
	s_nop 0
	global_load_lds_dwordx4 v230, s[48:49]
	s_add_i32 m0, s51, 0x4000
	s_nop 0
	global_load_lds_dwordx4 v229, s[48:49]
	s_add_i32 m0, s51, 0x4400
	s_nop 0
	global_load_lds_dwordx4 v231, s[48:49]
	v_add_u32_e32 v236, s40, v232
	v_add_u32_e32 v237, s40, v233
	ds_read_b128 v[188:191], v236
	ds_read_b128 v[196:199], v236 offset:2048
	ds_read_b128 v[200:203], v236 offset:4096
	ds_read_b128 v[204:207], v236 offset:6144
	ds_read_b128 v[212:215], v237
	ds_read_b128 v[216:219], v237 offset:2048
	ds_read_b128 v[220:223], v237 offset:4096
	ds_read_b128 v[224:227], v237 offset:6144
	s_waitcnt lgkmcnt(4)
	v_mfma_f32_16x16x32_bf16 v[66:69], v[136:139], v[188:191], v[66:69]
	v_mfma_f32_16x16x32_bf16 v[70:73], v[136:139], v[196:199], v[70:73]
	v_mfma_f32_16x16x32_bf16 v[74:77], v[136:139], v[200:203], v[74:77]
	v_mfma_f32_16x16x32_bf16 v[78:81], v[136:139], v[204:207], v[78:81]
	v_mfma_f32_16x16x32_bf16 v[82:85], v[140:143], v[188:191], v[82:85]
	v_mfma_f32_16x16x32_bf16 v[86:89], v[140:143], v[196:199], v[86:89]
	v_mfma_f32_16x16x32_bf16 v[90:93], v[140:143], v[200:203], v[90:93]
	v_mfma_f32_16x16x32_bf16 v[94:97], v[140:143], v[204:207], v[94:97]
	v_mfma_f32_16x16x32_bf16 v[98:101], v[144:147], v[188:191], v[98:101]
	v_mfma_f32_16x16x32_bf16 v[102:105], v[144:147], v[196:199], v[102:105]
	v_mfma_f32_16x16x32_bf16 v[106:109], v[144:147], v[200:203], v[106:109]
	v_mfma_f32_16x16x32_bf16 v[110:113], v[144:147], v[204:207], v[110:113]
	v_mfma_f32_16x16x32_bf16 v[114:117], v[148:151], v[188:191], v[114:117]
	v_mfma_f32_16x16x32_bf16 v[118:121], v[148:151], v[196:199], v[118:121]
	v_mfma_f32_16x16x32_bf16 v[122:125], v[148:151], v[200:203], v[122:125]
	v_mfma_f32_16x16x32_bf16 v[126:129], v[148:151], v[204:207], v[126:129]
	s_waitcnt lgkmcnt(0)
	v_mfma_f32_16x16x32_bf16 v[66:69], v[172:175], v[212:215], v[66:69]
	v_mfma_f32_16x16x32_bf16 v[70:73], v[172:175], v[216:219], v[70:73]
	v_mfma_f32_16x16x32_bf16 v[74:77], v[172:175], v[220:223], v[74:77]
	v_mfma_f32_16x16x32_bf16 v[78:81], v[172:175], v[224:227], v[78:81]
	v_mfma_f32_16x16x32_bf16 v[82:85], v[176:179], v[212:215], v[82:85]
	v_mfma_f32_16x16x32_bf16 v[86:89], v[176:179], v[216:219], v[86:89]
	v_mfma_f32_16x16x32_bf16 v[90:93], v[176:179], v[220:223], v[90:93]
	v_mfma_f32_16x16x32_bf16 v[94:97], v[176:179], v[224:227], v[94:97]
	v_mfma_f32_16x16x32_bf16 v[98:101], v[180:183], v[212:215], v[98:101]
	v_mfma_f32_16x16x32_bf16 v[102:105], v[180:183], v[216:219], v[102:105]
	v_mfma_f32_16x16x32_bf16 v[106:109], v[180:183], v[220:223], v[106:109]
	v_mfma_f32_16x16x32_bf16 v[110:113], v[180:183], v[224:227], v[110:113]
	v_mfma_f32_16x16x32_bf16 v[114:117], v[184:187], v[212:215], v[114:117]
	v_mfma_f32_16x16x32_bf16 v[118:121], v[184:187], v[216:219], v[118:121]
	v_mfma_f32_16x16x32_bf16 v[122:125], v[184:187], v[220:223], v[122:125]
	v_mfma_f32_16x16x32_bf16 v[126:129], v[184:187], v[224:227], v[126:129]
	v_add_u32_e32 v228, 0x80, v228
	v_add_u32_e32 v229, 0x80, v229
	v_add_u32_e32 v230, 0x80, v230
	v_add_u32_e32 v231, 0x80, v231
	s_waitcnt vmcnt(4)
	s_barrier
	v_add_u32_e32 v234, s23, v232
	v_add_u32_e32 v236, s29, v232
	v_add_u32_e32 v235, s23, v233
	v_add_u32_e32 v237, s29, v233
	ds_read_b128 v[136:139], v234
	ds_read_b128 v[140:143], v234 offset:2048
	ds_read_b128 v[144:147], v234 offset:4096
	ds_read_b128 v[148:151], v234 offset:6144
	ds_read_b128 v[188:191], v236
	ds_read_b128 v[196:199], v236 offset:2048
	ds_read_b128 v[200:203], v236 offset:4096
	ds_read_b128 v[204:207], v236 offset:6144
	ds_read_b128 v[172:175], v235
	ds_read_b128 v[176:179], v235 offset:2048
	ds_read_b128 v[180:183], v235 offset:4096
	ds_read_b128 v[184:187], v235 offset:6144
	ds_read_b128 v[212:215], v237
	ds_read_b128 v[216:219], v237 offset:2048
	ds_read_b128 v[220:223], v237 offset:4096
	ds_read_b128 v[224:227], v237 offset:6144
	s_waitcnt lgkmcnt(8)
	v_mfma_f32_16x16x32_bf16 v[2:5], v[136:139], v[188:191], v[2:5]
	v_mfma_f32_16x16x32_bf16 v[6:9], v[136:139], v[196:199], v[6:9]
	v_mfma_f32_16x16x32_bf16 v[10:13], v[136:139], v[200:203], v[10:13]
	v_mfma_f32_16x16x32_bf16 v[14:17], v[136:139], v[204:207], v[14:17]
	v_mfma_f32_16x16x32_bf16 v[18:21], v[140:143], v[188:191], v[18:21]
	v_mfma_f32_16x16x32_bf16 v[22:25], v[140:143], v[196:199], v[22:25]
	v_mfma_f32_16x16x32_bf16 v[26:29], v[140:143], v[200:203], v[26:29]
	v_mfma_f32_16x16x32_bf16 v[30:33], v[140:143], v[204:207], v[30:33]
	v_mfma_f32_16x16x32_bf16 v[34:37], v[144:147], v[188:191], v[34:37]
	v_mfma_f32_16x16x32_bf16 v[38:41], v[144:147], v[196:199], v[38:41]
	v_mfma_f32_16x16x32_bf16 v[42:45], v[144:147], v[200:203], v[42:45]
	v_mfma_f32_16x16x32_bf16 v[46:49], v[144:147], v[204:207], v[46:49]
	v_mfma_f32_16x16x32_bf16 v[50:53], v[148:151], v[188:191], v[50:53]
	v_mfma_f32_16x16x32_bf16 v[54:57], v[148:151], v[196:199], v[54:57]
	v_mfma_f32_16x16x32_bf16 v[58:61], v[148:151], v[200:203], v[58:61]
	v_mfma_f32_16x16x32_bf16 v[62:65], v[148:151], v[204:207], v[62:65]
	s_waitcnt lgkmcnt(0)
	v_mfma_f32_16x16x32_bf16 v[2:5], v[172:175], v[212:215], v[2:5]
	v_mfma_f32_16x16x32_bf16 v[6:9], v[172:175], v[216:219], v[6:9]
	v_mfma_f32_16x16x32_bf16 v[10:13], v[172:175], v[220:223], v[10:13]
	v_mfma_f32_16x16x32_bf16 v[14:17], v[172:175], v[224:227], v[14:17]
	v_mfma_f32_16x16x32_bf16 v[18:21], v[176:179], v[212:215], v[18:21]
	v_mfma_f32_16x16x32_bf16 v[22:25], v[176:179], v[216:219], v[22:25]
	v_mfma_f32_16x16x32_bf16 v[26:29], v[176:179], v[220:223], v[26:29]
	v_mfma_f32_16x16x32_bf16 v[30:33], v[176:179], v[224:227], v[30:33]
	v_mfma_f32_16x16x32_bf16 v[34:37], v[180:183], v[212:215], v[34:37]
	v_mfma_f32_16x16x32_bf16 v[38:41], v[180:183], v[216:219], v[38:41]
	v_mfma_f32_16x16x32_bf16 v[42:45], v[180:183], v[220:223], v[42:45]
	v_mfma_f32_16x16x32_bf16 v[46:49], v[180:183], v[224:227], v[46:49]
	v_mfma_f32_16x16x32_bf16 v[50:53], v[184:187], v[212:215], v[50:53]
	v_mfma_f32_16x16x32_bf16 v[54:57], v[184:187], v[216:219], v[54:57]
	v_mfma_f32_16x16x32_bf16 v[58:61], v[184:187], v[220:223], v[58:61]
	v_mfma_f32_16x16x32_bf16 v[62:65], v[184:187], v[224:227], v[62:65]
	s_waitcnt vmcnt(0)
	s_barrier
	v_add_u32_e32 v236, s41, v232
	v_add_u32_e32 v237, s41, v233
	ds_read_b128 v[188:191], v236
	ds_read_b128 v[196:199], v236 offset:2048
	ds_read_b128 v[200:203], v236 offset:4096
	ds_read_b128 v[204:207], v236 offset:6144
	ds_read_b128 v[212:215], v237
	ds_read_b128 v[216:219], v237 offset:2048
	ds_read_b128 v[220:223], v237 offset:4096
	ds_read_b128 v[224:227], v237 offset:6144
	s_waitcnt lgkmcnt(4)
	v_mfma_f32_16x16x32_bf16 v[66:69], v[136:139], v[188:191], v[66:69]
	v_mfma_f32_16x16x32_bf16 v[70:73], v[136:139], v[196:199], v[70:73]
	v_mfma_f32_16x16x32_bf16 v[74:77], v[136:139], v[200:203], v[74:77]
	v_mfma_f32_16x16x32_bf16 v[78:81], v[136:139], v[204:207], v[78:81]
	v_mfma_f32_16x16x32_bf16 v[82:85], v[140:143], v[188:191], v[82:85]
	v_mfma_f32_16x16x32_bf16 v[86:89], v[140:143], v[196:199], v[86:89]
	v_mfma_f32_16x16x32_bf16 v[90:93], v[140:143], v[200:203], v[90:93]
	v_mfma_f32_16x16x32_bf16 v[94:97], v[140:143], v[204:207], v[94:97]
	v_mfma_f32_16x16x32_bf16 v[98:101], v[144:147], v[188:191], v[98:101]
	v_mfma_f32_16x16x32_bf16 v[102:105], v[144:147], v[196:199], v[102:105]
	v_mfma_f32_16x16x32_bf16 v[106:109], v[144:147], v[200:203], v[106:109]
	v_mfma_f32_16x16x32_bf16 v[110:113], v[144:147], v[204:207], v[110:113]
	v_mfma_f32_16x16x32_bf16 v[114:117], v[148:151], v[188:191], v[114:117]
	v_mfma_f32_16x16x32_bf16 v[118:121], v[148:151], v[196:199], v[118:121]
	v_mfma_f32_16x16x32_bf16 v[122:125], v[148:151], v[200:203], v[122:125]
	v_mfma_f32_16x16x32_bf16 v[126:129], v[148:151], v[204:207], v[126:129]
	s_waitcnt lgkmcnt(0)
	v_mfma_f32_16x16x32_bf16 v[66:69], v[172:175], v[212:215], v[66:69]
	v_mfma_f32_16x16x32_bf16 v[70:73], v[172:175], v[216:219], v[70:73]
	v_mfma_f32_16x16x32_bf16 v[74:77], v[172:175], v[220:223], v[74:77]
	v_mfma_f32_16x16x32_bf16 v[78:81], v[172:175], v[224:227], v[78:81]
	v_mfma_f32_16x16x32_bf16 v[82:85], v[176:179], v[212:215], v[82:85]
	v_mfma_f32_16x16x32_bf16 v[86:89], v[176:179], v[216:219], v[86:89]
	v_mfma_f32_16x16x32_bf16 v[90:93], v[176:179], v[220:223], v[90:93]
	v_mfma_f32_16x16x32_bf16 v[94:97], v[176:179], v[224:227], v[94:97]
	v_mfma_f32_16x16x32_bf16 v[98:101], v[180:183], v[212:215], v[98:101]
	v_mfma_f32_16x16x32_bf16 v[102:105], v[180:183], v[216:219], v[102:105]
	v_mfma_f32_16x16x32_bf16 v[106:109], v[180:183], v[220:223], v[106:109]
	v_mfma_f32_16x16x32_bf16 v[110:113], v[180:183], v[224:227], v[110:113]
	v_mfma_f32_16x16x32_bf16 v[114:117], v[184:187], v[212:215], v[114:117]
	v_mfma_f32_16x16x32_bf16 v[118:121], v[184:187], v[216:219], v[118:121]
	v_mfma_f32_16x16x32_bf16 v[122:125], v[184:187], v[220:223], v[122:125]
	v_mfma_f32_16x16x32_bf16 v[126:129], v[184:187], v[224:227], v[126:129]
	s_nop 7
	s_barrier
	s_load_dwordx2 s[58:59], s[12:13], 0x180
	v_mov_b32_e32 v241, 0x3a000000
	v_mov_b32_e32 v242, 0x358637bd
	v_fma_f32 v152, v152, v241, v242
	v_fma_f32 v153, v153, v241, v242
	v_fma_f32 v154, v154, v241, v242
	v_fma_f32 v155, v155, v241, v242
	v_fma_f32 v244, v244, v241, v242
	v_fma_f32 v245, v245, v241, v242
	v_fma_f32 v246, v246, v241, v242
	v_fma_f32 v247, v247, v241, v242
	v_fma_f32 v248, v248, v241, v242
	v_fma_f32 v249, v249, v241, v242
	v_fma_f32 v250, v250, v241, v242
	v_fma_f32 v251, v251, v241, v242
	v_fma_f32 v252, v252, v241, v242
	v_fma_f32 v253, v253, v241, v242
	v_fma_f32 v254, v254, v241, v242
	v_fma_f32 v255, v255, v241, v242
	v_rsq_f32_e32 v152, v152
	v_rsq_f32_e32 v153, v153
	v_rsq_f32_e32 v154, v154
	v_rsq_f32_e32 v155, v155
	v_rsq_f32_e32 v244, v244
	v_rsq_f32_e32 v245, v245
	v_rsq_f32_e32 v246, v246
	v_rsq_f32_e32 v247, v247
	v_rsq_f32_e32 v248, v248
	v_rsq_f32_e32 v249, v249
	v_rsq_f32_e32 v250, v250
	v_rsq_f32_e32 v251, v251
	v_rsq_f32_e32 v252, v252
	v_rsq_f32_e32 v253, v253
	v_rsq_f32_e32 v254, v254
	v_rsq_f32_e32 v255, v255
	v_and_b32_e32 v241, 63, v131
	v_lshrrev_b32_e32 v242, 4, v241
	v_and_b32_e32 v241, 15, v241
	s_lshr_b32 s56, s50, 1
	s_and_b32 s57, s50, 1
	s_mul_i32 s56, s56, 64*144
	s_lshl_b32 s57, s57, 6
	s_add_i32 s56, s56, s57
	s_add_i32 s56, s56, 16
	v_mul_u32_u24_e32 v242, 4*144, v242
	v_lshl_add_u32 v242, v241, 1, v242
	v_add_u32_e32 v188, s56, v242
	v_lshrrev_b32_e32 v241, 3, v131
	v_and_b32_e32 v242, 7, v131
	v_lshlrev_b32_e32 v242, 4, v242
	v_mul_u32_u24_e32 v189, 144, v241
	v_add3_u32 v189, v189, v242, 16
	s_movk_i32 s56, 0x2c80
	v_mad_u32_u24 v243, v241, s56, v242
	s_mul_i32 s56, s53, 0x2c80
	s_add_i32 s56, s56, s54
	s_waitcnt lgkmcnt(0)
	s_add_u32 s58, s58, s56
	s_addc_u32 s59, s59, 0
	v_mul_f32_e32 v2, v2, v152
	v_mul_f32_e32 v6, v6, v152
	v_mul_f32_e32 v10, v10, v152
	v_mul_f32_e32 v14, v14, v152
	v_mul_f32_e32 v136, 0xbfb8aa3b, v2
	v_mul_f32_e32 v137, 0xbfb8aa3b, v6
	v_exp_f32_e32 v136, v136
	v_exp_f32_e32 v137, v137
	v_mul_f32_e32 v10, v10, v2
	v_mul_f32_e32 v14, v14, v6
	v_add_f32_e32 v136, 1.0, v136
	v_add_f32_e32 v137, 1.0, v137
	v_rcp_f32_e32 v136, v136
	v_rcp_f32_e32 v137, v137
	s_nop 0
	v_mul_f32_e32 v10, v10, v136
	v_mul_f32_e32 v14, v14, v137
	v_cvt_pk_bf16_f32 v10, v10, v14
	ds_write_b16 v188, v10
	ds_write_b16_d16_hi v188, v10 offset:32
	v_mul_f32_e32 v3, v3, v153
	v_mul_f32_e32 v7, v7, v153
	v_mul_f32_e32 v11, v11, v153
	v_mul_f32_e32 v15, v15, v153
	v_mul_f32_e32 v136, 0xbfb8aa3b, v3
	v_mul_f32_e32 v137, 0xbfb8aa3b, v7
	v_exp_f32_e32 v136, v136
	v_exp_f32_e32 v137, v137
	v_mul_f32_e32 v11, v11, v3
	v_mul_f32_e32 v15, v15, v7
	v_add_f32_e32 v136, 1.0, v136
	v_add_f32_e32 v137, 1.0, v137
	v_rcp_f32_e32 v136, v136
	v_rcp_f32_e32 v137, v137
	s_nop 0
	v_mul_f32_e32 v11, v11, v136
	v_mul_f32_e32 v15, v15, v137
	v_cvt_pk_bf16_f32 v11, v11, v15
	ds_write_b16 v188, v11 offset:144
	ds_write_b16_d16_hi v188, v11 offset:176
	v_mul_f32_e32 v4, v4, v154
	v_mul_f32_e32 v8, v8, v154
	v_mul_f32_e32 v12, v12, v154
	v_mul_f32_e32 v16, v16, v154
	v_mul_f32_e32 v136, 0xbfb8aa3b, v4
	v_mul_f32_e32 v137, 0xbfb8aa3b, v8
	v_exp_f32_e32 v136, v136
	v_exp_f32_e32 v137, v137
	v_mul_f32_e32 v12, v12, v4
	v_mul_f32_e32 v16, v16, v8
	v_add_f32_e32 v136, 1.0, v136
	v_add_f32_e32 v137, 1.0, v137
	v_rcp_f32_e32 v136, v136
	v_rcp_f32_e32 v137, v137
	s_nop 0
	v_mul_f32_e32 v12, v12, v136
	v_mul_f32_e32 v16, v16, v137
	v_cvt_pk_bf16_f32 v12, v12, v16
	ds_write_b16 v188, v12 offset:288
	ds_write_b16_d16_hi v188, v12 offset:320
	v_mul_f32_e32 v5, v5, v155
	v_mul_f32_e32 v9, v9, v155
	v_mul_f32_e32 v13, v13, v155
	v_mul_f32_e32 v17, v17, v155
	v_mul_f32_e32 v136, 0xbfb8aa3b, v5
	v_mul_f32_e32 v137, 0xbfb8aa3b, v9
	v_exp_f32_e32 v136, v136
	v_exp_f32_e32 v137, v137
	v_mul_f32_e32 v13, v13, v5
	v_mul_f32_e32 v17, v17, v9
	v_add_f32_e32 v136, 1.0, v136
	v_add_f32_e32 v137, 1.0, v137
	v_rcp_f32_e32 v136, v136
	v_rcp_f32_e32 v137, v137
	s_nop 0
	v_mul_f32_e32 v13, v13, v136
	v_mul_f32_e32 v17, v17, v137
	v_cvt_pk_bf16_f32 v13, v13, v17
	ds_write_b16 v188, v13 offset:432
	ds_write_b16_d16_hi v188, v13 offset:464
	v_mul_f32_e32 v18, v18, v244
	v_mul_f32_e32 v22, v22, v244
	v_mul_f32_e32 v26, v26, v244
	v_mul_f32_e32 v30, v30, v244
	v_mul_f32_e32 v136, 0xbfb8aa3b, v18
	v_mul_f32_e32 v137, 0xbfb8aa3b, v22
	v_exp_f32_e32 v136, v136
	v_exp_f32_e32 v137, v137
	v_mul_f32_e32 v26, v26, v18
	v_mul_f32_e32 v30, v30, v22
	v_add_f32_e32 v136, 1.0, v136
	v_add_f32_e32 v137, 1.0, v137
	v_rcp_f32_e32 v136, v136
	v_rcp_f32_e32 v137, v137
	s_nop 0
	v_mul_f32_e32 v26, v26, v136
	v_mul_f32_e32 v30, v30, v137
	v_cvt_pk_bf16_f32 v26, v26, v30
	ds_write_b16 v188, v26 offset:2304
	ds_write_b16_d16_hi v188, v26 offset:2336
	v_mul_f32_e32 v19, v19, v245
	v_mul_f32_e32 v23, v23, v245
	v_mul_f32_e32 v27, v27, v245
	v_mul_f32_e32 v31, v31, v245
	v_mul_f32_e32 v136, 0xbfb8aa3b, v19
	v_mul_f32_e32 v137, 0xbfb8aa3b, v23
	v_exp_f32_e32 v136, v136
	v_exp_f32_e32 v137, v137
	v_mul_f32_e32 v27, v27, v19
	v_mul_f32_e32 v31, v31, v23
	v_add_f32_e32 v136, 1.0, v136
	v_add_f32_e32 v137, 1.0, v137
	v_rcp_f32_e32 v136, v136
	v_rcp_f32_e32 v137, v137
	s_nop 0
	v_mul_f32_e32 v27, v27, v136
	v_mul_f32_e32 v31, v31, v137
	v_cvt_pk_bf16_f32 v27, v27, v31
	ds_write_b16 v188, v27 offset:2448
	ds_write_b16_d16_hi v188, v27 offset:2480
	v_mul_f32_e32 v20, v20, v246
	v_mul_f32_e32 v24, v24, v246
	v_mul_f32_e32 v28, v28, v246
	v_mul_f32_e32 v32, v32, v246
	v_mul_f32_e32 v136, 0xbfb8aa3b, v20
	v_mul_f32_e32 v137, 0xbfb8aa3b, v24
	v_exp_f32_e32 v136, v136
	v_exp_f32_e32 v137, v137
	v_mul_f32_e32 v28, v28, v20
	v_mul_f32_e32 v32, v32, v24
	v_add_f32_e32 v136, 1.0, v136
	v_add_f32_e32 v137, 1.0, v137
	v_rcp_f32_e32 v136, v136
	v_rcp_f32_e32 v137, v137
	s_nop 0
	v_mul_f32_e32 v28, v28, v136
	v_mul_f32_e32 v32, v32, v137
	v_cvt_pk_bf16_f32 v28, v28, v32
	ds_write_b16 v188, v28 offset:2592
	ds_write_b16_d16_hi v188, v28 offset:2624
	v_mul_f32_e32 v21, v21, v247
	v_mul_f32_e32 v25, v25, v247
	v_mul_f32_e32 v29, v29, v247
	v_mul_f32_e32 v33, v33, v247
	v_mul_f32_e32 v136, 0xbfb8aa3b, v21
	v_mul_f32_e32 v137, 0xbfb8aa3b, v25
	v_exp_f32_e32 v136, v136
	v_exp_f32_e32 v137, v137
	v_mul_f32_e32 v29, v29, v21
	v_mul_f32_e32 v33, v33, v25
	v_add_f32_e32 v136, 1.0, v136
	v_add_f32_e32 v137, 1.0, v137
	v_rcp_f32_e32 v136, v136
	v_rcp_f32_e32 v137, v137
	s_nop 0
	v_mul_f32_e32 v29, v29, v136
	v_mul_f32_e32 v33, v33, v137
	v_cvt_pk_bf16_f32 v29, v29, v33
	ds_write_b16 v188, v29 offset:2736
	ds_write_b16_d16_hi v188, v29 offset:2768
	v_mul_f32_e32 v34, v34, v248
	v_mul_f32_e32 v38, v38, v248
	v_mul_f32_e32 v42, v42, v248
	v_mul_f32_e32 v46, v46, v248
	v_mul_f32_e32 v136, 0xbfb8aa3b, v34
	v_mul_f32_e32 v137, 0xbfb8aa3b, v38
	v_exp_f32_e32 v136, v136
	v_exp_f32_e32 v137, v137
	v_mul_f32_e32 v42, v42, v34
	v_mul_f32_e32 v46, v46, v38
	v_add_f32_e32 v136, 1.0, v136
	v_add_f32_e32 v137, 1.0, v137
	v_rcp_f32_e32 v136, v136
	v_rcp_f32_e32 v137, v137
	s_nop 0
	v_mul_f32_e32 v42, v42, v136
	v_mul_f32_e32 v46, v46, v137
	v_cvt_pk_bf16_f32 v42, v42, v46
	ds_write_b16 v188, v42 offset:4608
	ds_write_b16_d16_hi v188, v42 offset:4640
	v_mul_f32_e32 v35, v35, v249
	v_mul_f32_e32 v39, v39, v249
	v_mul_f32_e32 v43, v43, v249
	v_mul_f32_e32 v47, v47, v249
	v_mul_f32_e32 v136, 0xbfb8aa3b, v35
	v_mul_f32_e32 v137, 0xbfb8aa3b, v39
	v_exp_f32_e32 v136, v136
	v_exp_f32_e32 v137, v137
	v_mul_f32_e32 v43, v43, v35
	v_mul_f32_e32 v47, v47, v39
	v_add_f32_e32 v136, 1.0, v136
	v_add_f32_e32 v137, 1.0, v137
	v_rcp_f32_e32 v136, v136
	v_rcp_f32_e32 v137, v137
	s_nop 0
	v_mul_f32_e32 v43, v43, v136
	v_mul_f32_e32 v47, v47, v137
	v_cvt_pk_bf16_f32 v43, v43, v47
	ds_write_b16 v188, v43 offset:4752
	ds_write_b16_d16_hi v188, v43 offset:4784
	v_mul_f32_e32 v36, v36, v250
	v_mul_f32_e32 v40, v40, v250
	v_mul_f32_e32 v44, v44, v250
	v_mul_f32_e32 v48, v48, v250
	v_mul_f32_e32 v136, 0xbfb8aa3b, v36
	v_mul_f32_e32 v137, 0xbfb8aa3b, v40
	v_exp_f32_e32 v136, v136
	v_exp_f32_e32 v137, v137
	v_mul_f32_e32 v44, v44, v36
	v_mul_f32_e32 v48, v48, v40
	v_add_f32_e32 v136, 1.0, v136
	v_add_f32_e32 v137, 1.0, v137
	v_rcp_f32_e32 v136, v136
	v_rcp_f32_e32 v137, v137
	s_nop 0
	v_mul_f32_e32 v44, v44, v136
	v_mul_f32_e32 v48, v48, v137
	v_cvt_pk_bf16_f32 v44, v44, v48
	ds_write_b16 v188, v44 offset:4896
	ds_write_b16_d16_hi v188, v44 offset:4928
	v_mul_f32_e32 v37, v37, v251
	v_mul_f32_e32 v41, v41, v251
	v_mul_f32_e32 v45, v45, v251
	v_mul_f32_e32 v49, v49, v251
	v_mul_f32_e32 v136, 0xbfb8aa3b, v37
	v_mul_f32_e32 v137, 0xbfb8aa3b, v41
	v_exp_f32_e32 v136, v136
	v_exp_f32_e32 v137, v137
	v_mul_f32_e32 v45, v45, v37
	v_mul_f32_e32 v49, v49, v41
	v_add_f32_e32 v136, 1.0, v136
	v_add_f32_e32 v137, 1.0, v137
	v_rcp_f32_e32 v136, v136
	v_rcp_f32_e32 v137, v137
	s_nop 0
	v_mul_f32_e32 v45, v45, v136
	v_mul_f32_e32 v49, v49, v137
	v_cvt_pk_bf16_f32 v45, v45, v49
	ds_write_b16 v188, v45 offset:5040
	ds_write_b16_d16_hi v188, v45 offset:5072
	v_mul_f32_e32 v50, v50, v252
	v_mul_f32_e32 v54, v54, v252
	v_mul_f32_e32 v58, v58, v252
	v_mul_f32_e32 v62, v62, v252
	v_mul_f32_e32 v136, 0xbfb8aa3b, v50
	v_mul_f32_e32 v137, 0xbfb8aa3b, v54
	v_exp_f32_e32 v136, v136
	v_exp_f32_e32 v137, v137
	v_mul_f32_e32 v58, v58, v50
	v_mul_f32_e32 v62, v62, v54
	v_add_f32_e32 v136, 1.0, v136
	v_add_f32_e32 v137, 1.0, v137
	v_rcp_f32_e32 v136, v136
	v_rcp_f32_e32 v137, v137
	s_nop 0
	v_mul_f32_e32 v58, v58, v136
	v_mul_f32_e32 v62, v62, v137
	v_cvt_pk_bf16_f32 v58, v58, v62
	ds_write_b16 v188, v58 offset:6912
	ds_write_b16_d16_hi v188, v58 offset:6944
	v_mul_f32_e32 v51, v51, v253
	v_mul_f32_e32 v55, v55, v253
	v_mul_f32_e32 v59, v59, v253
	v_mul_f32_e32 v63, v63, v253
	v_mul_f32_e32 v136, 0xbfb8aa3b, v51
	v_mul_f32_e32 v137, 0xbfb8aa3b, v55
	v_exp_f32_e32 v136, v136
	v_exp_f32_e32 v137, v137
	v_mul_f32_e32 v59, v59, v51
	v_mul_f32_e32 v63, v63, v55
	v_add_f32_e32 v136, 1.0, v136
	v_add_f32_e32 v137, 1.0, v137
	v_rcp_f32_e32 v136, v136
	v_rcp_f32_e32 v137, v137
	s_nop 0
	v_mul_f32_e32 v59, v59, v136
	v_mul_f32_e32 v63, v63, v137
	v_cvt_pk_bf16_f32 v59, v59, v63
	ds_write_b16 v188, v59 offset:7056
	ds_write_b16_d16_hi v188, v59 offset:7088
	v_mul_f32_e32 v52, v52, v254
	v_mul_f32_e32 v56, v56, v254
	v_mul_f32_e32 v60, v60, v254
	v_mul_f32_e32 v64, v64, v254
	v_mul_f32_e32 v136, 0xbfb8aa3b, v52
	v_mul_f32_e32 v137, 0xbfb8aa3b, v56
	v_exp_f32_e32 v136, v136
	v_exp_f32_e32 v137, v137
	v_mul_f32_e32 v60, v60, v52
	v_mul_f32_e32 v64, v64, v56
	v_add_f32_e32 v136, 1.0, v136
	v_add_f32_e32 v137, 1.0, v137
	v_rcp_f32_e32 v136, v136
	v_rcp_f32_e32 v137, v137
	s_nop 0
	v_mul_f32_e32 v60, v60, v136
	v_mul_f32_e32 v64, v64, v137
	v_cvt_pk_bf16_f32 v60, v60, v64
	ds_write_b16 v188, v60 offset:7200
	ds_write_b16_d16_hi v188, v60 offset:7232
	v_mul_f32_e32 v53, v53, v255
	v_mul_f32_e32 v57, v57, v255
	v_mul_f32_e32 v61, v61, v255
	v_mul_f32_e32 v65, v65, v255
	v_mul_f32_e32 v136, 0xbfb8aa3b, v53
	v_mul_f32_e32 v137, 0xbfb8aa3b, v57
	v_exp_f32_e32 v136, v136
	v_exp_f32_e32 v137, v137
	v_mul_f32_e32 v61, v61, v53
	v_mul_f32_e32 v65, v65, v57
	v_add_f32_e32 v136, 1.0, v136
	v_add_f32_e32 v137, 1.0, v137
	v_rcp_f32_e32 v136, v136
	v_rcp_f32_e32 v137, v137
	s_nop 0
	v_mul_f32_e32 v61, v61, v136
	v_mul_f32_e32 v65, v65, v137
	v_cvt_pk_bf16_f32 v61, v61, v65
	ds_write_b16 v188, v61 offset:7344
	ds_write_b16_d16_hi v188, v61 offset:7376
	s_waitcnt lgkmcnt(0)
	s_barrier
	ds_read_b128 v[144:147], v189
	ds_read_b128 v[148:151], v189 offset:4608
	ds_read_b128 v[172:175], v189 offset:9216
	ds_read_b128 v[176:179], v189 offset:13824
	s_mov_b32 s56, s58
	s_mov_b32 s57, s59
	s_waitcnt lgkmcnt(3)
	global_store_dwordx4 v243, v[144:147], s[56:57]
	s_add_u32 s56, s56, 0x59000
	s_addc_u32 s57, s57, 0
	s_waitcnt lgkmcnt(2)
	global_store_dwordx4 v243, v[148:151], s[56:57]
	s_add_u32 s56, s56, 0x59000
	s_addc_u32 s57, s57, 0
	s_waitcnt lgkmcnt(1)
	global_store_dwordx4 v243, v[172:175], s[56:57]
	s_add_u32 s56, s56, 0x59000
	s_addc_u32 s57, s57, 0
	s_waitcnt lgkmcnt(0)
	global_store_dwordx4 v243, v[176:179], s[56:57]
	s_add_u32 s58, s58, 0x400
	s_addc_u32 s59, s59, 0
	s_barrier
	v_mul_f32_e32 v66, v66, v152
	v_mul_f32_e32 v70, v70, v152
	v_mul_f32_e32 v74, v74, v152
	v_mul_f32_e32 v78, v78, v152
	v_mul_f32_e32 v136, 0xbfb8aa3b, v66
	v_mul_f32_e32 v137, 0xbfb8aa3b, v70
	v_exp_f32_e32 v136, v136
	v_exp_f32_e32 v137, v137
	v_mul_f32_e32 v74, v74, v66
	v_mul_f32_e32 v78, v78, v70
	v_add_f32_e32 v136, 1.0, v136
	v_add_f32_e32 v137, 1.0, v137
	v_rcp_f32_e32 v136, v136
	v_rcp_f32_e32 v137, v137
	s_nop 0
	v_mul_f32_e32 v74, v74, v136
	v_mul_f32_e32 v78, v78, v137
	v_cvt_pk_bf16_f32 v74, v74, v78
	ds_write_b16 v188, v74
	ds_write_b16_d16_hi v188, v74 offset:32
	v_mul_f32_e32 v67, v67, v153
	v_mul_f32_e32 v71, v71, v153
	v_mul_f32_e32 v75, v75, v153
	v_mul_f32_e32 v79, v79, v153
	v_mul_f32_e32 v136, 0xbfb8aa3b, v67
	v_mul_f32_e32 v137, 0xbfb8aa3b, v71
	v_exp_f32_e32 v136, v136
	v_exp_f32_e32 v137, v137
	v_mul_f32_e32 v75, v75, v67
	v_mul_f32_e32 v79, v79, v71
	v_add_f32_e32 v136, 1.0, v136
	v_add_f32_e32 v137, 1.0, v137
	v_rcp_f32_e32 v136, v136
	v_rcp_f32_e32 v137, v137
	s_nop 0
	v_mul_f32_e32 v75, v75, v136
	v_mul_f32_e32 v79, v79, v137
	v_cvt_pk_bf16_f32 v75, v75, v79
	ds_write_b16 v188, v75 offset:144
	ds_write_b16_d16_hi v188, v75 offset:176
	v_mul_f32_e32 v68, v68, v154
	v_mul_f32_e32 v72, v72, v154
	v_mul_f32_e32 v76, v76, v154
	v_mul_f32_e32 v80, v80, v154
	v_mul_f32_e32 v136, 0xbfb8aa3b, v68
	v_mul_f32_e32 v137, 0xbfb8aa3b, v72
	v_exp_f32_e32 v136, v136
	v_exp_f32_e32 v137, v137
	v_mul_f32_e32 v76, v76, v68
	v_mul_f32_e32 v80, v80, v72
	v_add_f32_e32 v136, 1.0, v136
	v_add_f32_e32 v137, 1.0, v137
	v_rcp_f32_e32 v136, v136
	v_rcp_f32_e32 v137, v137
	s_nop 0
	v_mul_f32_e32 v76, v76, v136
	v_mul_f32_e32 v80, v80, v137
	v_cvt_pk_bf16_f32 v76, v76, v80
	ds_write_b16 v188, v76 offset:288
	ds_write_b16_d16_hi v188, v76 offset:320
	v_mul_f32_e32 v69, v69, v155
	v_mul_f32_e32 v73, v73, v155
	v_mul_f32_e32 v77, v77, v155
	v_mul_f32_e32 v81, v81, v155
	v_mul_f32_e32 v136, 0xbfb8aa3b, v69
	v_mul_f32_e32 v137, 0xbfb8aa3b, v73
	v_exp_f32_e32 v136, v136
	v_exp_f32_e32 v137, v137
	v_mul_f32_e32 v77, v77, v69
	v_mul_f32_e32 v81, v81, v73
	v_add_f32_e32 v136, 1.0, v136
	v_add_f32_e32 v137, 1.0, v137
	v_rcp_f32_e32 v136, v136
	v_rcp_f32_e32 v137, v137
	s_nop 0
	v_mul_f32_e32 v77, v77, v136
	v_mul_f32_e32 v81, v81, v137
	v_cvt_pk_bf16_f32 v77, v77, v81
	ds_write_b16 v188, v77 offset:432
	ds_write_b16_d16_hi v188, v77 offset:464
	v_mul_f32_e32 v82, v82, v244
	v_mul_f32_e32 v86, v86, v244
	v_mul_f32_e32 v90, v90, v244
	v_mul_f32_e32 v94, v94, v244
	v_mul_f32_e32 v136, 0xbfb8aa3b, v82
	v_mul_f32_e32 v137, 0xbfb8aa3b, v86
	v_exp_f32_e32 v136, v136
	v_exp_f32_e32 v137, v137
	v_mul_f32_e32 v90, v90, v82
	v_mul_f32_e32 v94, v94, v86
	v_add_f32_e32 v136, 1.0, v136
	v_add_f32_e32 v137, 1.0, v137
	v_rcp_f32_e32 v136, v136
	v_rcp_f32_e32 v137, v137
	s_nop 0
	v_mul_f32_e32 v90, v90, v136
	v_mul_f32_e32 v94, v94, v137
	v_cvt_pk_bf16_f32 v90, v90, v94
	ds_write_b16 v188, v90 offset:2304
	ds_write_b16_d16_hi v188, v90 offset:2336
	v_mul_f32_e32 v83, v83, v245
	v_mul_f32_e32 v87, v87, v245
	v_mul_f32_e32 v91, v91, v245
	v_mul_f32_e32 v95, v95, v245
	v_mul_f32_e32 v136, 0xbfb8aa3b, v83
	v_mul_f32_e32 v137, 0xbfb8aa3b, v87
	v_exp_f32_e32 v136, v136
	v_exp_f32_e32 v137, v137
	v_mul_f32_e32 v91, v91, v83
	v_mul_f32_e32 v95, v95, v87
	v_add_f32_e32 v136, 1.0, v136
	v_add_f32_e32 v137, 1.0, v137
	v_rcp_f32_e32 v136, v136
	v_rcp_f32_e32 v137, v137
	s_nop 0
	v_mul_f32_e32 v91, v91, v136
	v_mul_f32_e32 v95, v95, v137
	v_cvt_pk_bf16_f32 v91, v91, v95
	ds_write_b16 v188, v91 offset:2448
	ds_write_b16_d16_hi v188, v91 offset:2480
	v_mul_f32_e32 v84, v84, v246
	v_mul_f32_e32 v88, v88, v246
	v_mul_f32_e32 v92, v92, v246
	v_mul_f32_e32 v96, v96, v246
	v_mul_f32_e32 v136, 0xbfb8aa3b, v84
	v_mul_f32_e32 v137, 0xbfb8aa3b, v88
	v_exp_f32_e32 v136, v136
	v_exp_f32_e32 v137, v137
	v_mul_f32_e32 v92, v92, v84
	v_mul_f32_e32 v96, v96, v88
	v_add_f32_e32 v136, 1.0, v136
	v_add_f32_e32 v137, 1.0, v137
	v_rcp_f32_e32 v136, v136
	v_rcp_f32_e32 v137, v137
	s_nop 0
	v_mul_f32_e32 v92, v92, v136
	v_mul_f32_e32 v96, v96, v137
	v_cvt_pk_bf16_f32 v92, v92, v96
	ds_write_b16 v188, v92 offset:2592
	ds_write_b16_d16_hi v188, v92 offset:2624
	v_mul_f32_e32 v85, v85, v247
	v_mul_f32_e32 v89, v89, v247
	v_mul_f32_e32 v93, v93, v247
	v_mul_f32_e32 v97, v97, v247
	v_mul_f32_e32 v136, 0xbfb8aa3b, v85
	v_mul_f32_e32 v137, 0xbfb8aa3b, v89
	v_exp_f32_e32 v136, v136
	v_exp_f32_e32 v137, v137
	v_mul_f32_e32 v93, v93, v85
	v_mul_f32_e32 v97, v97, v89
	v_add_f32_e32 v136, 1.0, v136
	v_add_f32_e32 v137, 1.0, v137
	v_rcp_f32_e32 v136, v136
	v_rcp_f32_e32 v137, v137
	s_nop 0
	v_mul_f32_e32 v93, v93, v136
	v_mul_f32_e32 v97, v97, v137
	v_cvt_pk_bf16_f32 v93, v93, v97
	ds_write_b16 v188, v93 offset:2736
	ds_write_b16_d16_hi v188, v93 offset:2768
	v_mul_f32_e32 v98, v98, v248
	v_mul_f32_e32 v102, v102, v248
	v_mul_f32_e32 v106, v106, v248
	v_mul_f32_e32 v110, v110, v248
	v_mul_f32_e32 v136, 0xbfb8aa3b, v98
	v_mul_f32_e32 v137, 0xbfb8aa3b, v102
	v_exp_f32_e32 v136, v136
	v_exp_f32_e32 v137, v137
	v_mul_f32_e32 v106, v106, v98
	v_mul_f32_e32 v110, v110, v102
	v_add_f32_e32 v136, 1.0, v136
	v_add_f32_e32 v137, 1.0, v137
	v_rcp_f32_e32 v136, v136
	v_rcp_f32_e32 v137, v137
	s_nop 0
	v_mul_f32_e32 v106, v106, v136
	v_mul_f32_e32 v110, v110, v137
	v_cvt_pk_bf16_f32 v106, v106, v110
	ds_write_b16 v188, v106 offset:4608
	ds_write_b16_d16_hi v188, v106 offset:4640
	v_mul_f32_e32 v99, v99, v249
	v_mul_f32_e32 v103, v103, v249
	v_mul_f32_e32 v107, v107, v249
	v_mul_f32_e32 v111, v111, v249
	v_mul_f32_e32 v136, 0xbfb8aa3b, v99
	v_mul_f32_e32 v137, 0xbfb8aa3b, v103
	v_exp_f32_e32 v136, v136
	v_exp_f32_e32 v137, v137
	v_mul_f32_e32 v107, v107, v99
	v_mul_f32_e32 v111, v111, v103
	v_add_f32_e32 v136, 1.0, v136
	v_add_f32_e32 v137, 1.0, v137
	v_rcp_f32_e32 v136, v136
	v_rcp_f32_e32 v137, v137
	s_nop 0
	v_mul_f32_e32 v107, v107, v136
	v_mul_f32_e32 v111, v111, v137
	v_cvt_pk_bf16_f32 v107, v107, v111
	ds_write_b16 v188, v107 offset:4752
	ds_write_b16_d16_hi v188, v107 offset:4784
	v_mul_f32_e32 v100, v100, v250
	v_mul_f32_e32 v104, v104, v250
	v_mul_f32_e32 v108, v108, v250
	v_mul_f32_e32 v112, v112, v250
	v_mul_f32_e32 v136, 0xbfb8aa3b, v100
	v_mul_f32_e32 v137, 0xbfb8aa3b, v104
	v_exp_f32_e32 v136, v136
	v_exp_f32_e32 v137, v137
	v_mul_f32_e32 v108, v108, v100
	v_mul_f32_e32 v112, v112, v104
	v_add_f32_e32 v136, 1.0, v136
	v_add_f32_e32 v137, 1.0, v137
	v_rcp_f32_e32 v136, v136
	v_rcp_f32_e32 v137, v137
	s_nop 0
	v_mul_f32_e32 v108, v108, v136
	v_mul_f32_e32 v112, v112, v137
	v_cvt_pk_bf16_f32 v108, v108, v112
	ds_write_b16 v188, v108 offset:4896
	ds_write_b16_d16_hi v188, v108 offset:4928
	v_mul_f32_e32 v101, v101, v251
	v_mul_f32_e32 v105, v105, v251
	v_mul_f32_e32 v109, v109, v251
	v_mul_f32_e32 v113, v113, v251
	v_mul_f32_e32 v136, 0xbfb8aa3b, v101
	v_mul_f32_e32 v137, 0xbfb8aa3b, v105
	v_exp_f32_e32 v136, v136
	v_exp_f32_e32 v137, v137
	v_mul_f32_e32 v109, v109, v101
	v_mul_f32_e32 v113, v113, v105
	v_add_f32_e32 v136, 1.0, v136
	v_add_f32_e32 v137, 1.0, v137
	v_rcp_f32_e32 v136, v136
	v_rcp_f32_e32 v137, v137
	s_nop 0
	v_mul_f32_e32 v109, v109, v136
	v_mul_f32_e32 v113, v113, v137
	v_cvt_pk_bf16_f32 v109, v109, v113
	ds_write_b16 v188, v109 offset:5040
	ds_write_b16_d16_hi v188, v109 offset:5072
	v_mul_f32_e32 v114, v114, v252
	v_mul_f32_e32 v118, v118, v252
	v_mul_f32_e32 v122, v122, v252
	v_mul_f32_e32 v126, v126, v252
	v_mul_f32_e32 v136, 0xbfb8aa3b, v114
	v_mul_f32_e32 v137, 0xbfb8aa3b, v118
	v_exp_f32_e32 v136, v136
	v_exp_f32_e32 v137, v137
	v_mul_f32_e32 v122, v122, v114
	v_mul_f32_e32 v126, v126, v118
	v_add_f32_e32 v136, 1.0, v136
	v_add_f32_e32 v137, 1.0, v137
	v_rcp_f32_e32 v136, v136
	v_rcp_f32_e32 v137, v137
	s_nop 0
	v_mul_f32_e32 v122, v122, v136
	v_mul_f32_e32 v126, v126, v137
	v_cvt_pk_bf16_f32 v122, v122, v126
	ds_write_b16 v188, v122 offset:6912
	ds_write_b16_d16_hi v188, v122 offset:6944
	v_mul_f32_e32 v115, v115, v253
	v_mul_f32_e32 v119, v119, v253
	v_mul_f32_e32 v123, v123, v253
	v_mul_f32_e32 v127, v127, v253
	v_mul_f32_e32 v136, 0xbfb8aa3b, v115
	v_mul_f32_e32 v137, 0xbfb8aa3b, v119
	v_exp_f32_e32 v136, v136
	v_exp_f32_e32 v137, v137
	v_mul_f32_e32 v123, v123, v115
	v_mul_f32_e32 v127, v127, v119
	v_add_f32_e32 v136, 1.0, v136
	v_add_f32_e32 v137, 1.0, v137
	v_rcp_f32_e32 v136, v136
	v_rcp_f32_e32 v137, v137
	s_nop 0
	v_mul_f32_e32 v123, v123, v136
	v_mul_f32_e32 v127, v127, v137
	v_cvt_pk_bf16_f32 v123, v123, v127
	ds_write_b16 v188, v123 offset:7056
	ds_write_b16_d16_hi v188, v123 offset:7088
	v_mul_f32_e32 v116, v116, v254
	v_mul_f32_e32 v120, v120, v254
	v_mul_f32_e32 v124, v124, v254
	v_mul_f32_e32 v128, v128, v254
	v_mul_f32_e32 v136, 0xbfb8aa3b, v116
	v_mul_f32_e32 v137, 0xbfb8aa3b, v120
	v_exp_f32_e32 v136, v136
	v_exp_f32_e32 v137, v137
	v_mul_f32_e32 v124, v124, v116
	v_mul_f32_e32 v128, v128, v120
	v_add_f32_e32 v136, 1.0, v136
	v_add_f32_e32 v137, 1.0, v137
	v_rcp_f32_e32 v136, v136
	v_rcp_f32_e32 v137, v137
	s_nop 0
	v_mul_f32_e32 v124, v124, v136
	v_mul_f32_e32 v128, v128, v137
	v_cvt_pk_bf16_f32 v124, v124, v128
	ds_write_b16 v188, v124 offset:7200
	ds_write_b16_d16_hi v188, v124 offset:7232
	v_mul_f32_e32 v117, v117, v255
	v_mul_f32_e32 v121, v121, v255
	v_mul_f32_e32 v125, v125, v255
	v_mul_f32_e32 v129, v129, v255
	v_mul_f32_e32 v136, 0xbfb8aa3b, v117
	v_mul_f32_e32 v137, 0xbfb8aa3b, v121
	v_exp_f32_e32 v136, v136
	v_exp_f32_e32 v137, v137
	v_mul_f32_e32 v125, v125, v117
	v_mul_f32_e32 v129, v129, v121
	v_add_f32_e32 v136, 1.0, v136
	v_add_f32_e32 v137, 1.0, v137
	v_rcp_f32_e32 v136, v136
	v_rcp_f32_e32 v137, v137
	s_nop 0
	v_mul_f32_e32 v125, v125, v136
	v_mul_f32_e32 v129, v129, v137
	v_cvt_pk_bf16_f32 v125, v125, v129
	ds_write_b16 v188, v125 offset:7344
	ds_write_b16_d16_hi v188, v125 offset:7376
	s_waitcnt lgkmcnt(0)
	s_barrier
	ds_read_b128 v[144:147], v189
	ds_read_b128 v[148:151], v189 offset:4608
	ds_read_b128 v[172:175], v189 offset:9216
	ds_read_b128 v[176:179], v189 offset:13824
	s_mov_b32 s56, s58
	s_mov_b32 s57, s59
	s_waitcnt lgkmcnt(3)
	global_store_dwordx4 v243, v[144:147], s[56:57]
	s_add_u32 s56, s56, 0x59000
	s_addc_u32 s57, s57, 0
	s_waitcnt lgkmcnt(2)
	global_store_dwordx4 v243, v[148:151], s[56:57]
	s_add_u32 s56, s56, 0x59000
	s_addc_u32 s57, s57, 0
	s_waitcnt lgkmcnt(1)
	global_store_dwordx4 v243, v[172:175], s[56:57]
	s_add_u32 s56, s56, 0x59000
	s_addc_u32 s57, s57, 0
	s_waitcnt lgkmcnt(0)
	global_store_dwordx4 v243, v[176:179], s[56:57]
	s_add_i32 s55, s55, 1
	s_cmp_lt_u32 s55, 5
	s_barrier
	s_cbranch_scc1 .Lgu2_tile
	s_add_i32 s21, s21, s72
	s_cmpk_lt_i32 s21, 0x200
	s_cbranch_scc1 .Lgu2_vloop
.Lgu2_done:
	s_cmpk_gt_i32 s60, 0x1ff
	s_cbranch_scc1 .LBB0_97
	s_add_i32 s20, s60, 0x1400
	s_lshl_b32 s8, s20, 7
	s_branch .LBB0_93
